# v118 with s_setprio 3 (instead of 1) around the MFMA groups of the custom double-tile GEMM loops
# speedup vs baseline: 1.0043x; 1.0043x over previous
.Lg2_k:
	s_waitcnt vmcnt(0)
	s_barrier
	s_add_i32 m0, s58, 0xc000
	s_nop 0
	global_load_lds_dwordx4 v74, s[56:57]
	s_add_i32 m0, s58, 0xd000
	s_nop 0
	global_load_lds_dwordx4 v75, s[56:57]
	s_add_i32 m0, s58, 0xe000
	s_nop 0
	global_load_lds_dwordx4 v76, s[56:57]
	s_add_i32 m0, s58, 0xf000
	s_nop 0
	global_load_lds_dwordx4 v77, s[56:57]
	s_add_u32 s56, s56, 0x80
	s_addc_u32 s57, s57, 0
	ds_read_b128 v[148:151], v78 offset:0
	ds_read_b128 v[152:155], v78 offset:2048
	ds_read_b128 v[156:159], v78 offset:4096
	ds_read_b128 v[160:163], v78 offset:6144
	ds_read_b128 v[188:191], v79 offset:32768
	ds_read_b128 v[192:195], v79 offset:34816
	ds_read_b128 v[208:211], v79 offset:36864
	ds_read_b128 v[212:215], v79 offset:38912
	ds_read_b128 v[164:167], v78 offset:16384
	ds_read_b128 v[168:171], v78 offset:18432
	ds_read_b128 v[174:177], v78 offset:20480
	ds_read_b128 v[182:185], v78 offset:22528
	s_setprio 3
	s_waitcnt lgkmcnt(4)
	v_mfma_f32_16x16x32_bf16 v[62:65], v[188:191], v[148:151], v[62:65]
	v_mfma_f32_16x16x32_bf16 v[58:61], v[192:195], v[148:151], v[58:61]
	v_mfma_f32_16x16x32_bf16 v[54:57], v[208:211], v[148:151], v[54:57]
	v_mfma_f32_16x16x32_bf16 v[50:53], v[212:215], v[148:151], v[50:53]
	v_mfma_f32_16x16x32_bf16 v[46:49], v[188:191], v[152:155], v[46:49]
	v_mfma_f32_16x16x32_bf16 v[42:45], v[192:195], v[152:155], v[42:45]
	v_mfma_f32_16x16x32_bf16 v[38:41], v[208:211], v[152:155], v[38:41]
	v_mfma_f32_16x16x32_bf16 v[34:37], v[212:215], v[152:155], v[34:37]
	v_mfma_f32_16x16x32_bf16 v[30:33], v[188:191], v[156:159], v[30:33]
	v_mfma_f32_16x16x32_bf16 v[26:29], v[192:195], v[156:159], v[26:29]
	v_mfma_f32_16x16x32_bf16 v[22:25], v[208:211], v[156:159], v[22:25]
	v_mfma_f32_16x16x32_bf16 v[18:21], v[212:215], v[156:159], v[18:21]
	v_mfma_f32_16x16x32_bf16 v[14:17], v[188:191], v[160:163], v[14:17]
	v_mfma_f32_16x16x32_bf16 v[10:13], v[192:195], v[160:163], v[10:13]
	v_mfma_f32_16x16x32_bf16 v[6:9], v[208:211], v[160:163], v[6:9]
	v_mfma_f32_16x16x32_bf16 v[2:5], v[212:215], v[160:163], v[2:5]
	s_waitcnt lgkmcnt(0)
	v_mfma_f32_16x16x32_bf16 v[66:69], v[188:191], v[164:167], v[66:69]
	v_mfma_f32_16x16x32_bf16 v[70:73], v[192:195], v[164:167], v[70:73]
	v_mfma_f32_16x16x32_bf16 v[82:85], v[208:211], v[164:167], v[82:85]
	v_mfma_f32_16x16x32_bf16 v[88:91], v[212:215], v[164:167], v[88:91]
	v_mfma_f32_16x16x32_bf16 v[92:95], v[188:191], v[168:171], v[92:95]
	v_mfma_f32_16x16x32_bf16 v[96:99], v[192:195], v[168:171], v[96:99]
	v_mfma_f32_16x16x32_bf16 v[100:103], v[208:211], v[168:171], v[100:103]
	v_mfma_f32_16x16x32_bf16 v[106:109], v[212:215], v[168:171], v[106:109]
	v_mfma_f32_16x16x32_bf16 v[110:113], v[188:191], v[174:177], v[110:113]
	v_mfma_f32_16x16x32_bf16 v[114:117], v[192:195], v[174:177], v[114:117]
	v_mfma_f32_16x16x32_bf16 v[118:121], v[208:211], v[174:177], v[118:121]
	v_mfma_f32_16x16x32_bf16 v[122:125], v[212:215], v[174:177], v[122:125]
	v_mfma_f32_16x16x32_bf16 v[126:129], v[188:191], v[182:185], v[126:129]
	v_mfma_f32_16x16x32_bf16 v[136:139], v[192:195], v[182:185], v[136:139]
	v_mfma_f32_16x16x32_bf16 v[140:143], v[208:211], v[182:185], v[140:143]
	v_mfma_f32_16x16x32_bf16 v[144:147], v[212:215], v[182:185], v[144:147]
	s_setprio 0
	ds_read_b128 v[148:151], v80 offset:0
	ds_read_b128 v[152:155], v80 offset:2048
	ds_read_b128 v[156:159], v80 offset:4096
	ds_read_b128 v[160:163], v80 offset:6144
	ds_read_b128 v[188:191], v81 offset:32768
	ds_read_b128 v[192:195], v81 offset:34816
	ds_read_b128 v[208:211], v81 offset:36864
	ds_read_b128 v[212:215], v81 offset:38912
	ds_read_b128 v[164:167], v80 offset:16384
	ds_read_b128 v[168:171], v80 offset:18432
	ds_read_b128 v[174:177], v80 offset:20480
	ds_read_b128 v[182:185], v80 offset:22528
	s_waitcnt lgkmcnt(0)
	s_barrier
	s_add_i32 m0, s58, 0x0
	s_nop 0
	global_load_lds_dwordx4 v74, s[50:51]
	s_add_i32 m0, s58, 0x1000
	s_nop 0
	global_load_lds_dwordx4 v75, s[50:51]
	s_add_i32 m0, s58, 0x2000
	s_nop 0
	global_load_lds_dwordx4 v76, s[50:51]
	s_add_i32 m0, s58, 0x3000
	s_nop 0
	global_load_lds_dwordx4 v77, s[50:51]
	s_add_i32 m0, s58, 0x4000
	s_nop 0
	global_load_lds_dwordx4 v74, s[52:53]
	s_add_i32 m0, s58, 0x5000
	s_nop 0
	global_load_lds_dwordx4 v75, s[52:53]
	s_add_i32 m0, s58, 0x6000
	s_nop 0
	global_load_lds_dwordx4 v76, s[52:53]
	s_add_i32 m0, s58, 0x7000
	s_nop 0
	global_load_lds_dwordx4 v77, s[52:53]
	s_add_u32 s50, s50, 0x80
	s_addc_u32 s51, s51, 0
	s_add_u32 s52, s52, 0x80
	s_addc_u32 s53, s53, 0
	s_setprio 3
	v_mfma_f32_16x16x32_bf16 v[62:65], v[188:191], v[148:151], v[62:65]
	v_mfma_f32_16x16x32_bf16 v[58:61], v[192:195], v[148:151], v[58:61]
	v_mfma_f32_16x16x32_bf16 v[54:57], v[208:211], v[148:151], v[54:57]
	v_mfma_f32_16x16x32_bf16 v[50:53], v[212:215], v[148:151], v[50:53]
	v_mfma_f32_16x16x32_bf16 v[46:49], v[188:191], v[152:155], v[46:49]
	v_mfma_f32_16x16x32_bf16 v[42:45], v[192:195], v[152:155], v[42:45]
	v_mfma_f32_16x16x32_bf16 v[38:41], v[208:211], v[152:155], v[38:41]
	v_mfma_f32_16x16x32_bf16 v[34:37], v[212:215], v[152:155], v[34:37]
	v_mfma_f32_16x16x32_bf16 v[30:33], v[188:191], v[156:159], v[30:33]
	v_mfma_f32_16x16x32_bf16 v[26:29], v[192:195], v[156:159], v[26:29]
	v_mfma_f32_16x16x32_bf16 v[22:25], v[208:211], v[156:159], v[22:25]
	v_mfma_f32_16x16x32_bf16 v[18:21], v[212:215], v[156:159], v[18:21]
	v_mfma_f32_16x16x32_bf16 v[14:17], v[188:191], v[160:163], v[14:17]
	v_mfma_f32_16x16x32_bf16 v[10:13], v[192:195], v[160:163], v[10:13]
	v_mfma_f32_16x16x32_bf16 v[6:9], v[208:211], v[160:163], v[6:9]
	v_mfma_f32_16x16x32_bf16 v[2:5], v[212:215], v[160:163], v[2:5]
	v_mfma_f32_16x16x32_bf16 v[66:69], v[188:191], v[164:167], v[66:69]
	v_mfma_f32_16x16x32_bf16 v[70:73], v[192:195], v[164:167], v[70:73]
	v_mfma_f32_16x16x32_bf16 v[82:85], v[208:211], v[164:167], v[82:85]
	v_mfma_f32_16x16x32_bf16 v[88:91], v[212:215], v[164:167], v[88:91]
	v_mfma_f32_16x16x32_bf16 v[92:95], v[188:191], v[168:171], v[92:95]
	v_mfma_f32_16x16x32_bf16 v[96:99], v[192:195], v[168:171], v[96:99]
	v_mfma_f32_16x16x32_bf16 v[100:103], v[208:211], v[168:171], v[100:103]
	v_mfma_f32_16x16x32_bf16 v[106:109], v[212:215], v[168:171], v[106:109]
	v_mfma_f32_16x16x32_bf16 v[110:113], v[188:191], v[174:177], v[110:113]
	v_mfma_f32_16x16x32_bf16 v[114:117], v[192:195], v[174:177], v[114:117]
	v_mfma_f32_16x16x32_bf16 v[118:121], v[208:211], v[174:177], v[118:121]
	v_mfma_f32_16x16x32_bf16 v[122:125], v[212:215], v[174:177], v[122:125]
	v_mfma_f32_16x16x32_bf16 v[126:129], v[188:191], v[182:185], v[126:129]
	v_mfma_f32_16x16x32_bf16 v[136:139], v[192:195], v[182:185], v[136:139]
	v_mfma_f32_16x16x32_bf16 v[140:143], v[208:211], v[182:185], v[140:143]
	v_mfma_f32_16x16x32_bf16 v[144:147], v[212:215], v[182:185], v[144:147]
	s_setprio 0
	s_waitcnt vmcnt(0)
	s_barrier
	s_add_i32 m0, s58, 0x8000
	s_nop 0
	global_load_lds_dwordx4 v74, s[56:57]
	s_add_i32 m0, s58, 0x9000
	s_nop 0
	global_load_lds_dwordx4 v75, s[56:57]
	s_add_i32 m0, s58, 0xa000
	s_nop 0
	global_load_lds_dwordx4 v76, s[56:57]
	s_add_i32 m0, s58, 0xb000
	s_nop 0
	global_load_lds_dwordx4 v77, s[56:57]
	s_add_u32 s56, s56, 0x80
	s_addc_u32 s57, s57, 0
	ds_read_b128 v[148:151], v78 offset:0
	ds_read_b128 v[152:155], v78 offset:2048
	ds_read_b128 v[156:159], v78 offset:4096
	ds_read_b128 v[160:163], v78 offset:6144
	ds_read_b128 v[188:191], v79 offset:49152
	ds_read_b128 v[192:195], v79 offset:51200
	ds_read_b128 v[208:211], v79 offset:53248
	ds_read_b128 v[212:215], v79 offset:55296
	ds_read_b128 v[164:167], v78 offset:16384
	ds_read_b128 v[168:171], v78 offset:18432
	ds_read_b128 v[174:177], v78 offset:20480
	ds_read_b128 v[182:185], v78 offset:22528
	s_setprio 3
	s_waitcnt lgkmcnt(4)
	v_mfma_f32_16x16x32_bf16 v[62:65], v[188:191], v[148:151], v[62:65]
	v_mfma_f32_16x16x32_bf16 v[58:61], v[192:195], v[148:151], v[58:61]
	v_mfma_f32_16x16x32_bf16 v[54:57], v[208:211], v[148:151], v[54:57]
	v_mfma_f32_16x16x32_bf16 v[50:53], v[212:215], v[148:151], v[50:53]
	v_mfma_f32_16x16x32_bf16 v[46:49], v[188:191], v[152:155], v[46:49]
	v_mfma_f32_16x16x32_bf16 v[42:45], v[192:195], v[152:155], v[42:45]
	v_mfma_f32_16x16x32_bf16 v[38:41], v[208:211], v[152:155], v[38:41]
	v_mfma_f32_16x16x32_bf16 v[34:37], v[212:215], v[152:155], v[34:37]
	v_mfma_f32_16x16x32_bf16 v[30:33], v[188:191], v[156:159], v[30:33]
	v_mfma_f32_16x16x32_bf16 v[26:29], v[192:195], v[156:159], v[26:29]
	v_mfma_f32_16x16x32_bf16 v[22:25], v[208:211], v[156:159], v[22:25]
	v_mfma_f32_16x16x32_bf16 v[18:21], v[212:215], v[156:159], v[18:21]
	v_mfma_f32_16x16x32_bf16 v[14:17], v[188:191], v[160:163], v[14:17]
	v_mfma_f32_16x16x32_bf16 v[10:13], v[192:195], v[160:163], v[10:13]
	v_mfma_f32_16x16x32_bf16 v[6:9], v[208:211], v[160:163], v[6:9]
	v_mfma_f32_16x16x32_bf16 v[2:5], v[212:215], v[160:163], v[2:5]
	s_waitcnt lgkmcnt(0)
	v_mfma_f32_16x16x32_bf16 v[66:69], v[188:191], v[164:167], v[66:69]
	v_mfma_f32_16x16x32_bf16 v[70:73], v[192:195], v[164:167], v[70:73]
	v_mfma_f32_16x16x32_bf16 v[82:85], v[208:211], v[164:167], v[82:85]
	v_mfma_f32_16x16x32_bf16 v[88:91], v[212:215], v[164:167], v[88:91]
	v_mfma_f32_16x16x32_bf16 v[92:95], v[188:191], v[168:171], v[92:95]
	v_mfma_f32_16x16x32_bf16 v[96:99], v[192:195], v[168:171], v[96:99]
	v_mfma_f32_16x16x32_bf16 v[100:103], v[208:211], v[168:171], v[100:103]
	v_mfma_f32_16x16x32_bf16 v[106:109], v[212:215], v[168:171], v[106:109]
	v_mfma_f32_16x16x32_bf16 v[110:113], v[188:191], v[174:177], v[110:113]
	v_mfma_f32_16x16x32_bf16 v[114:117], v[192:195], v[174:177], v[114:117]
	v_mfma_f32_16x16x32_bf16 v[118:121], v[208:211], v[174:177], v[118:121]
	v_mfma_f32_16x16x32_bf16 v[122:125], v[212:215], v[174:177], v[122:125]
	v_mfma_f32_16x16x32_bf16 v[126:129], v[188:191], v[182:185], v[126:129]
	v_mfma_f32_16x16x32_bf16 v[136:139], v[192:195], v[182:185], v[136:139]
	v_mfma_f32_16x16x32_bf16 v[140:143], v[208:211], v[182:185], v[140:143]
	v_mfma_f32_16x16x32_bf16 v[144:147], v[212:215], v[182:185], v[144:147]
	s_setprio 0
	ds_read_b128 v[148:151], v80 offset:0
	ds_read_b128 v[152:155], v80 offset:2048
	ds_read_b128 v[156:159], v80 offset:4096
	ds_read_b128 v[160:163], v80 offset:6144
	ds_read_b128 v[188:191], v81 offset:49152
	ds_read_b128 v[192:195], v81 offset:51200
	ds_read_b128 v[208:211], v81 offset:53248
	ds_read_b128 v[212:215], v81 offset:55296
	ds_read_b128 v[164:167], v80 offset:16384
	ds_read_b128 v[168:171], v80 offset:18432
	ds_read_b128 v[174:177], v80 offset:20480
	ds_read_b128 v[182:185], v80 offset:22528
	s_waitcnt lgkmcnt(0)
	s_barrier
	s_add_i32 m0, s58, 0x0
	s_nop 0
	global_load_lds_dwordx4 v74, s[50:51]
	s_add_i32 m0, s58, 0x1000
	s_nop 0
	global_load_lds_dwordx4 v75, s[50:51]
	s_add_i32 m0, s58, 0x2000
	s_nop 0
	global_load_lds_dwordx4 v76, s[50:51]
	s_add_i32 m0, s58, 0x3000
	s_nop 0
	global_load_lds_dwordx4 v77, s[50:51]
	s_add_i32 m0, s58, 0x4000
	s_nop 0
	global_load_lds_dwordx4 v74, s[52:53]
	s_add_i32 m0, s58, 0x5000
	s_nop 0
	global_load_lds_dwordx4 v75, s[52:53]
	s_add_i32 m0, s58, 0x6000
	s_nop 0
	global_load_lds_dwordx4 v76, s[52:53]
	s_add_i32 m0, s58, 0x7000
	s_nop 0
	global_load_lds_dwordx4 v77, s[52:53]
	s_add_u32 s50, s50, 0x80
	s_addc_u32 s51, s51, 0
	s_add_u32 s52, s52, 0x80
	s_addc_u32 s53, s53, 0
	s_setprio 3
	v_mfma_f32_16x16x32_bf16 v[62:65], v[188:191], v[148:151], v[62:65]
	v_mfma_f32_16x16x32_bf16 v[58:61], v[192:195], v[148:151], v[58:61]
	v_mfma_f32_16x16x32_bf16 v[54:57], v[208:211], v[148:151], v[54:57]
	v_mfma_f32_16x16x32_bf16 v[50:53], v[212:215], v[148:151], v[50:53]
	v_mfma_f32_16x16x32_bf16 v[46:49], v[188:191], v[152:155], v[46:49]
	v_mfma_f32_16x16x32_bf16 v[42:45], v[192:195], v[152:155], v[42:45]
	v_mfma_f32_16x16x32_bf16 v[38:41], v[208:211], v[152:155], v[38:41]
	v_mfma_f32_16x16x32_bf16 v[34:37], v[212:215], v[152:155], v[34:37]
	v_mfma_f32_16x16x32_bf16 v[30:33], v[188:191], v[156:159], v[30:33]
	v_mfma_f32_16x16x32_bf16 v[26:29], v[192:195], v[156:159], v[26:29]
	v_mfma_f32_16x16x32_bf16 v[22:25], v[208:211], v[156:159], v[22:25]
	v_mfma_f32_16x16x32_bf16 v[18:21], v[212:215], v[156:159], v[18:21]
	v_mfma_f32_16x16x32_bf16 v[14:17], v[188:191], v[160:163], v[14:17]
	v_mfma_f32_16x16x32_bf16 v[10:13], v[192:195], v[160:163], v[10:13]
	v_mfma_f32_16x16x32_bf16 v[6:9], v[208:211], v[160:163], v[6:9]
	v_mfma_f32_16x16x32_bf16 v[2:5], v[212:215], v[160:163], v[2:5]
	v_mfma_f32_16x16x32_bf16 v[66:69], v[188:191], v[164:167], v[66:69]
	v_mfma_f32_16x16x32_bf16 v[70:73], v[192:195], v[164:167], v[70:73]
	v_mfma_f32_16x16x32_bf16 v[82:85], v[208:211], v[164:167], v[82:85]
	v_mfma_f32_16x16x32_bf16 v[88:91], v[212:215], v[164:167], v[88:91]
	v_mfma_f32_16x16x32_bf16 v[92:95], v[188:191], v[168:171], v[92:95]
	v_mfma_f32_16x16x32_bf16 v[96:99], v[192:195], v[168:171], v[96:99]
	v_mfma_f32_16x16x32_bf16 v[100:103], v[208:211], v[168:171], v[100:103]
	v_mfma_f32_16x16x32_bf16 v[106:109], v[212:215], v[168:171], v[106:109]
	v_mfma_f32_16x16x32_bf16 v[110:113], v[188:191], v[174:177], v[110:113]
	v_mfma_f32_16x16x32_bf16 v[114:117], v[192:195], v[174:177], v[114:117]
	v_mfma_f32_16x16x32_bf16 v[118:121], v[208:211], v[174:177], v[118:121]
	v_mfma_f32_16x16x32_bf16 v[122:125], v[212:215], v[174:177], v[122:125]
	v_mfma_f32_16x16x32_bf16 v[126:129], v[188:191], v[182:185], v[126:129]
	v_mfma_f32_16x16x32_bf16 v[136:139], v[192:195], v[182:185], v[136:139]
	v_mfma_f32_16x16x32_bf16 v[140:143], v[208:211], v[182:185], v[140:143]
	v_mfma_f32_16x16x32_bf16 v[144:147], v[212:215], v[182:185], v[144:147]
	s_setprio 0
	s_add_i32 s59, s59, -1
	s_cmp_lg_u32 s59, 0
	s_cbranch_scc1 .Lg2_k
	s_waitcnt vmcnt(0)
	s_barrier
	s_add_i32 m0, s58, 0xc000
	s_nop 0
	global_load_lds_dwordx4 v74, s[56:57]
	s_add_i32 m0, s58, 0xd000
	s_nop 0
	global_load_lds_dwordx4 v75, s[56:57]
	s_add_i32 m0, s58, 0xe000
	s_nop 0
	global_load_lds_dwordx4 v76, s[56:57]
	s_add_i32 m0, s58, 0xf000
	s_nop 0
	global_load_lds_dwordx4 v77, s[56:57]
	s_add_u32 s56, s56, 0x80
	s_addc_u32 s57, s57, 0
	ds_read_b128 v[148:151], v78 offset:0
	ds_read_b128 v[152:155], v78 offset:2048
	ds_read_b128 v[156:159], v78 offset:4096
	ds_read_b128 v[160:163], v78 offset:6144
	ds_read_b128 v[188:191], v79 offset:32768
	ds_read_b128 v[192:195], v79 offset:34816
	ds_read_b128 v[208:211], v79 offset:36864
	ds_read_b128 v[212:215], v79 offset:38912
	ds_read_b128 v[164:167], v78 offset:16384
	ds_read_b128 v[168:171], v78 offset:18432
	ds_read_b128 v[174:177], v78 offset:20480
	ds_read_b128 v[182:185], v78 offset:22528
	s_setprio 3
	s_waitcnt lgkmcnt(4)
	v_mfma_f32_16x16x32_bf16 v[62:65], v[188:191], v[148:151], v[62:65]
	v_mfma_f32_16x16x32_bf16 v[58:61], v[192:195], v[148:151], v[58:61]
	v_mfma_f32_16x16x32_bf16 v[54:57], v[208:211], v[148:151], v[54:57]
	v_mfma_f32_16x16x32_bf16 v[50:53], v[212:215], v[148:151], v[50:53]
	v_mfma_f32_16x16x32_bf16 v[46:49], v[188:191], v[152:155], v[46:49]
	v_mfma_f32_16x16x32_bf16 v[42:45], v[192:195], v[152:155], v[42:45]
	v_mfma_f32_16x16x32_bf16 v[38:41], v[208:211], v[152:155], v[38:41]
	v_mfma_f32_16x16x32_bf16 v[34:37], v[212:215], v[152:155], v[34:37]
	v_mfma_f32_16x16x32_bf16 v[30:33], v[188:191], v[156:159], v[30:33]
	v_mfma_f32_16x16x32_bf16 v[26:29], v[192:195], v[156:159], v[26:29]
	v_mfma_f32_16x16x32_bf16 v[22:25], v[208:211], v[156:159], v[22:25]
	v_mfma_f32_16x16x32_bf16 v[18:21], v[212:215], v[156:159], v[18:21]
	v_mfma_f32_16x16x32_bf16 v[14:17], v[188:191], v[160:163], v[14:17]
	v_mfma_f32_16x16x32_bf16 v[10:13], v[192:195], v[160:163], v[10:13]
	v_mfma_f32_16x16x32_bf16 v[6:9], v[208:211], v[160:163], v[6:9]
	v_mfma_f32_16x16x32_bf16 v[2:5], v[212:215], v[160:163], v[2:5]
	s_waitcnt lgkmcnt(0)
	v_mfma_f32_16x16x32_bf16 v[66:69], v[188:191], v[164:167], v[66:69]
	v_mfma_f32_16x16x32_bf16 v[70:73], v[192:195], v[164:167], v[70:73]
	v_mfma_f32_16x16x32_bf16 v[82:85], v[208:211], v[164:167], v[82:85]
	v_mfma_f32_16x16x32_bf16 v[88:91], v[212:215], v[164:167], v[88:91]
	v_mfma_f32_16x16x32_bf16 v[92:95], v[188:191], v[168:171], v[92:95]
	v_mfma_f32_16x16x32_bf16 v[96:99], v[192:195], v[168:171], v[96:99]
	v_mfma_f32_16x16x32_bf16 v[100:103], v[208:211], v[168:171], v[100:103]
	v_mfma_f32_16x16x32_bf16 v[106:109], v[212:215], v[168:171], v[106:109]
	v_mfma_f32_16x16x32_bf16 v[110:113], v[188:191], v[174:177], v[110:113]
	v_mfma_f32_16x16x32_bf16 v[114:117], v[192:195], v[174:177], v[114:117]
	v_mfma_f32_16x16x32_bf16 v[118:121], v[208:211], v[174:177], v[118:121]
	v_mfma_f32_16x16x32_bf16 v[122:125], v[212:215], v[174:177], v[122:125]
	v_mfma_f32_16x16x32_bf16 v[126:129], v[188:191], v[182:185], v[126:129]
	v_mfma_f32_16x16x32_bf16 v[136:139], v[192:195], v[182:185], v[136:139]
	v_mfma_f32_16x16x32_bf16 v[140:143], v[208:211], v[182:185], v[140:143]
	v_mfma_f32_16x16x32_bf16 v[144:147], v[212:215], v[182:185], v[144:147]
	s_setprio 0
	ds_read_b128 v[148:151], v80 offset:0
	ds_read_b128 v[152:155], v80 offset:2048
	ds_read_b128 v[156:159], v80 offset:4096
	ds_read_b128 v[160:163], v80 offset:6144
	ds_read_b128 v[188:191], v81 offset:32768
	ds_read_b128 v[192:195], v81 offset:34816
	ds_read_b128 v[208:211], v81 offset:36864
	ds_read_b128 v[212:215], v81 offset:38912
	ds_read_b128 v[164:167], v80 offset:16384
	ds_read_b128 v[168:171], v80 offset:18432
	ds_read_b128 v[174:177], v80 offset:20480
	ds_read_b128 v[182:185], v80 offset:22528
	s_waitcnt lgkmcnt(0)
	s_barrier
	s_add_i32 m0, s58, 0x0
	s_nop 0
	global_load_lds_dwordx4 v74, s[50:51]
	s_add_i32 m0, s58, 0x1000
	s_nop 0
	global_load_lds_dwordx4 v75, s[50:51]
	s_add_i32 m0, s58, 0x2000
	s_nop 0
	global_load_lds_dwordx4 v76, s[50:51]
	s_add_i32 m0, s58, 0x3000
	s_nop 0
	global_load_lds_dwordx4 v77, s[50:51]
	s_add_i32 m0, s58, 0x4000
	s_nop 0
	global_load_lds_dwordx4 v74, s[52:53]
	s_add_i32 m0, s58, 0x5000
	s_nop 0
	global_load_lds_dwordx4 v75, s[52:53]
	s_add_i32 m0, s58, 0x6000
	s_nop 0
	global_load_lds_dwordx4 v76, s[52:53]
	s_add_i32 m0, s58, 0x7000
	s_nop 0
	global_load_lds_dwordx4 v77, s[52:53]
	s_add_u32 s50, s50, 0x80
	s_addc_u32 s51, s51, 0
	s_add_u32 s52, s52, 0x80
	s_addc_u32 s53, s53, 0
	s_setprio 3
	v_mfma_f32_16x16x32_bf16 v[62:65], v[188:191], v[148:151], v[62:65]
	v_mfma_f32_16x16x32_bf16 v[58:61], v[192:195], v[148:151], v[58:61]
	v_mfma_f32_16x16x32_bf16 v[54:57], v[208:211], v[148:151], v[54:57]
	v_mfma_f32_16x16x32_bf16 v[50:53], v[212:215], v[148:151], v[50:53]
	v_mfma_f32_16x16x32_bf16 v[46:49], v[188:191], v[152:155], v[46:49]
	v_mfma_f32_16x16x32_bf16 v[42:45], v[192:195], v[152:155], v[42:45]
	v_mfma_f32_16x16x32_bf16 v[38:41], v[208:211], v[152:155], v[38:41]
	v_mfma_f32_16x16x32_bf16 v[34:37], v[212:215], v[152:155], v[34:37]
	v_mfma_f32_16x16x32_bf16 v[30:33], v[188:191], v[156:159], v[30:33]
	v_mfma_f32_16x16x32_bf16 v[26:29], v[192:195], v[156:159], v[26:29]
	v_mfma_f32_16x16x32_bf16 v[22:25], v[208:211], v[156:159], v[22:25]
	v_mfma_f32_16x16x32_bf16 v[18:21], v[212:215], v[156:159], v[18:21]
	v_mfma_f32_16x16x32_bf16 v[14:17], v[188:191], v[160:163], v[14:17]
	v_mfma_f32_16x16x32_bf16 v[10:13], v[192:195], v[160:163], v[10:13]
	v_mfma_f32_16x16x32_bf16 v[6:9], v[208:211], v[160:163], v[6:9]
	v_mfma_f32_16x16x32_bf16 v[2:5], v[212:215], v[160:163], v[2:5]
	v_mfma_f32_16x16x32_bf16 v[66:69], v[188:191], v[164:167], v[66:69]
	v_mfma_f32_16x16x32_bf16 v[70:73], v[192:195], v[164:167], v[70:73]
	v_mfma_f32_16x16x32_bf16 v[82:85], v[208:211], v[164:167], v[82:85]
	v_mfma_f32_16x16x32_bf16 v[88:91], v[212:215], v[164:167], v[88:91]
	v_mfma_f32_16x16x32_bf16 v[92:95], v[188:191], v[168:171], v[92:95]
	v_mfma_f32_16x16x32_bf16 v[96:99], v[192:195], v[168:171], v[96:99]
	v_mfma_f32_16x16x32_bf16 v[100:103], v[208:211], v[168:171], v[100:103]
	v_mfma_f32_16x16x32_bf16 v[106:109], v[212:215], v[168:171], v[106:109]
	v_mfma_f32_16x16x32_bf16 v[110:113], v[188:191], v[174:177], v[110:113]
	v_mfma_f32_16x16x32_bf16 v[114:117], v[192:195], v[174:177], v[114:117]
	v_mfma_f32_16x16x32_bf16 v[118:121], v[208:211], v[174:177], v[118:121]
	v_mfma_f32_16x16x32_bf16 v[122:125], v[212:215], v[174:177], v[122:125]
	v_mfma_f32_16x16x32_bf16 v[126:129], v[188:191], v[182:185], v[126:129]
	v_mfma_f32_16x16x32_bf16 v[136:139], v[192:195], v[182:185], v[136:139]
	v_mfma_f32_16x16x32_bf16 v[140:143], v[208:211], v[182:185], v[140:143]
	v_mfma_f32_16x16x32_bf16 v[144:147], v[212:215], v[182:185], v[144:147]
	s_setprio 0
	s_waitcnt vmcnt(0)
	s_barrier
	ds_read_b128 v[148:151], v78 offset:0
	ds_read_b128 v[152:155], v78 offset:2048
	ds_read_b128 v[156:159], v78 offset:4096
	ds_read_b128 v[160:163], v78 offset:6144
	ds_read_b128 v[188:191], v79 offset:49152
	ds_read_b128 v[192:195], v79 offset:51200
	ds_read_b128 v[208:211], v79 offset:53248
	ds_read_b128 v[212:215], v79 offset:55296
	ds_read_b128 v[164:167], v78 offset:16384
	ds_read_b128 v[168:171], v78 offset:18432
	ds_read_b128 v[174:177], v78 offset:20480
	ds_read_b128 v[182:185], v78 offset:22528
	s_setprio 3
	s_waitcnt lgkmcnt(4)
	v_mfma_f32_16x16x32_bf16 v[62:65], v[188:191], v[148:151], v[62:65]
	v_mfma_f32_16x16x32_bf16 v[58:61], v[192:195], v[148:151], v[58:61]
	v_mfma_f32_16x16x32_bf16 v[54:57], v[208:211], v[148:151], v[54:57]
	v_mfma_f32_16x16x32_bf16 v[50:53], v[212:215], v[148:151], v[50:53]
	v_mfma_f32_16x16x32_bf16 v[46:49], v[188:191], v[152:155], v[46:49]
	v_mfma_f32_16x16x32_bf16 v[42:45], v[192:195], v[152:155], v[42:45]
	v_mfma_f32_16x16x32_bf16 v[38:41], v[208:211], v[152:155], v[38:41]
	v_mfma_f32_16x16x32_bf16 v[34:37], v[212:215], v[152:155], v[34:37]
	v_mfma_f32_16x16x32_bf16 v[30:33], v[188:191], v[156:159], v[30:33]
	v_mfma_f32_16x16x32_bf16 v[26:29], v[192:195], v[156:159], v[26:29]
	v_mfma_f32_16x16x32_bf16 v[22:25], v[208:211], v[156:159], v[22:25]
	v_mfma_f32_16x16x32_bf16 v[18:21], v[212:215], v[156:159], v[18:21]
	v_mfma_f32_16x16x32_bf16 v[14:17], v[188:191], v[160:163], v[14:17]
	v_mfma_f32_16x16x32_bf16 v[10:13], v[192:195], v[160:163], v[10:13]
	v_mfma_f32_16x16x32_bf16 v[6:9], v[208:211], v[160:163], v[6:9]
	v_mfma_f32_16x16x32_bf16 v[2:5], v[212:215], v[160:163], v[2:5]
	s_waitcnt lgkmcnt(0)
	v_mfma_f32_16x16x32_bf16 v[66:69], v[188:191], v[164:167], v[66:69]
	v_mfma_f32_16x16x32_bf16 v[70:73], v[192:195], v[164:167], v[70:73]
	v_mfma_f32_16x16x32_bf16 v[82:85], v[208:211], v[164:167], v[82:85]
	v_mfma_f32_16x16x32_bf16 v[88:91], v[212:215], v[164:167], v[88:91]
	v_mfma_f32_16x16x32_bf16 v[92:95], v[188:191], v[168:171], v[92:95]
	v_mfma_f32_16x16x32_bf16 v[96:99], v[192:195], v[168:171], v[96:99]
	v_mfma_f32_16x16x32_bf16 v[100:103], v[208:211], v[168:171], v[100:103]
	v_mfma_f32_16x16x32_bf16 v[106:109], v[212:215], v[168:171], v[106:109]
	v_mfma_f32_16x16x32_bf16 v[110:113], v[188:191], v[174:177], v[110:113]
	v_mfma_f32_16x16x32_bf16 v[114:117], v[192:195], v[174:177], v[114:117]
	v_mfma_f32_16x16x32_bf16 v[118:121], v[208:211], v[174:177], v[118:121]
	v_mfma_f32_16x16x32_bf16 v[122:125], v[212:215], v[174:177], v[122:125]
	v_mfma_f32_16x16x32_bf16 v[126:129], v[188:191], v[182:185], v[126:129]
	v_mfma_f32_16x16x32_bf16 v[136:139], v[192:195], v[182:185], v[136:139]
	v_mfma_f32_16x16x32_bf16 v[140:143], v[208:211], v[182:185], v[140:143]
	v_mfma_f32_16x16x32_bf16 v[144:147], v[212:215], v[182:185], v[144:147]
	s_setprio 0
	ds_read_b128 v[148:151], v80 offset:0
	ds_read_b128 v[152:155], v80 offset:2048
	ds_read_b128 v[156:159], v80 offset:4096
	ds_read_b128 v[160:163], v80 offset:6144
	ds_read_b128 v[188:191], v81 offset:49152
	ds_read_b128 v[192:195], v81 offset:51200
	ds_read_b128 v[208:211], v81 offset:53248
	ds_read_b128 v[212:215], v81 offset:55296
	ds_read_b128 v[164:167], v80 offset:16384
	ds_read_b128 v[168:171], v80 offset:18432
	ds_read_b128 v[174:177], v80 offset:20480
	ds_read_b128 v[182:185], v80 offset:22528
	s_setprio 3
	s_waitcnt lgkmcnt(4)
	v_mfma_f32_16x16x32_bf16 v[62:65], v[188:191], v[148:151], v[62:65]
	v_mfma_f32_16x16x32_bf16 v[58:61], v[192:195], v[148:151], v[58:61]
	v_mfma_f32_16x16x32_bf16 v[54:57], v[208:211], v[148:151], v[54:57]
	v_mfma_f32_16x16x32_bf16 v[50:53], v[212:215], v[148:151], v[50:53]
	v_mfma_f32_16x16x32_bf16 v[46:49], v[188:191], v[152:155], v[46:49]
	v_mfma_f32_16x16x32_bf16 v[42:45], v[192:195], v[152:155], v[42:45]
	v_mfma_f32_16x16x32_bf16 v[38:41], v[208:211], v[152:155], v[38:41]
	v_mfma_f32_16x16x32_bf16 v[34:37], v[212:215], v[152:155], v[34:37]
	v_mfma_f32_16x16x32_bf16 v[30:33], v[188:191], v[156:159], v[30:33]
	v_mfma_f32_16x16x32_bf16 v[26:29], v[192:195], v[156:159], v[26:29]
	v_mfma_f32_16x16x32_bf16 v[22:25], v[208:211], v[156:159], v[22:25]
	v_mfma_f32_16x16x32_bf16 v[18:21], v[212:215], v[156:159], v[18:21]
	v_mfma_f32_16x16x32_bf16 v[14:17], v[188:191], v[160:163], v[14:17]
	v_mfma_f32_16x16x32_bf16 v[10:13], v[192:195], v[160:163], v[10:13]
	v_mfma_f32_16x16x32_bf16 v[6:9], v[208:211], v[160:163], v[6:9]
	v_mfma_f32_16x16x32_bf16 v[2:5], v[212:215], v[160:163], v[2:5]
	s_waitcnt lgkmcnt(0)
	v_mfma_f32_16x16x32_bf16 v[66:69], v[188:191], v[164:167], v[66:69]
	v_mfma_f32_16x16x32_bf16 v[70:73], v[192:195], v[164:167], v[70:73]
	v_mfma_f32_16x16x32_bf16 v[82:85], v[208:211], v[164:167], v[82:85]
	v_mfma_f32_16x16x32_bf16 v[88:91], v[212:215], v[164:167], v[88:91]
	v_mfma_f32_16x16x32_bf16 v[92:95], v[188:191], v[168:171], v[92:95]
	v_mfma_f32_16x16x32_bf16 v[96:99], v[192:195], v[168:171], v[96:99]
	v_mfma_f32_16x16x32_bf16 v[100:103], v[208:211], v[168:171], v[100:103]
	v_mfma_f32_16x16x32_bf16 v[106:109], v[212:215], v[168:171], v[106:109]
	v_mfma_f32_16x16x32_bf16 v[110:113], v[188:191], v[174:177], v[110:113]
	v_mfma_f32_16x16x32_bf16 v[114:117], v[192:195], v[174:177], v[114:117]
	v_mfma_f32_16x16x32_bf16 v[118:121], v[208:211], v[174:177], v[118:121]
	v_mfma_f32_16x16x32_bf16 v[122:125], v[212:215], v[174:177], v[122:125]
	v_mfma_f32_16x16x32_bf16 v[126:129], v[188:191], v[182:185], v[126:129]
	v_mfma_f32_16x16x32_bf16 v[136:139], v[192:195], v[182:185], v[136:139]
	v_mfma_f32_16x16x32_bf16 v[140:143], v[208:211], v[182:185], v[140:143]
	v_mfma_f32_16x16x32_bf16 v[144:147], v[212:215], v[182:185], v[144:147]
	s_setprio 0
	s_nop 7
	s_nop 7
	s_nop 7
	v_mov_b32_e32 v148, v66
	v_mov_b32_e32 v149, v67
	v_mov_b32_e32 v150, v68
	v_mov_b32_e32 v151, v69
	v_mov_b32_e32 v152, v70
	v_mov_b32_e32 v153, v71
	v_mov_b32_e32 v154, v72
	v_mov_b32_e32 v155, v73
	v_mov_b32_e32 v156, v82
	v_mov_b32_e32 v157, v83
	v_mov_b32_e32 v158, v84
	v_mov_b32_e32 v159, v85
	v_mov_b32_e32 v160, v88
	v_mov_b32_e32 v161, v89
	v_mov_b32_e32 v162, v90
	v_mov_b32_e32 v163, v91
	v_mov_b32_e32 v164, v92
	v_mov_b32_e32 v165, v93
	v_mov_b32_e32 v166, v94
	v_mov_b32_e32 v167, v95
	v_mov_b32_e32 v168, v96
	v_mov_b32_e32 v169, v97
	v_mov_b32_e32 v170, v98
	v_mov_b32_e32 v171, v99
	v_mov_b32_e32 v174, v100
	v_mov_b32_e32 v175, v101
	v_mov_b32_e32 v176, v102
	v_mov_b32_e32 v177, v103
	v_mov_b32_e32 v182, v106
	v_mov_b32_e32 v183, v107
	v_mov_b32_e32 v184, v108
	v_mov_b32_e32 v185, v109
	v_mov_b32_e32 v188, v110
	v_mov_b32_e32 v189, v111
	v_mov_b32_e32 v190, v112
	v_mov_b32_e32 v191, v113
	v_mov_b32_e32 v192, v114
	v_mov_b32_e32 v193, v115
	v_mov_b32_e32 v194, v116
	v_mov_b32_e32 v195, v117
	v_mov_b32_e32 v208, v118
	v_mov_b32_e32 v209, v119
	v_mov_b32_e32 v210, v120
	v_mov_b32_e32 v211, v121
	v_mov_b32_e32 v212, v122
	v_mov_b32_e32 v213, v123
	v_mov_b32_e32 v214, v124
	v_mov_b32_e32 v215, v125
	v_mov_b32_e32 v216, v126
	v_mov_b32_e32 v217, v127
	v_mov_b32_e32 v218, v128
	v_mov_b32_e32 v219, v129
	v_mov_b32_e32 v220, v136
	v_mov_b32_e32 v221, v137
	v_mov_b32_e32 v222, v138
	v_mov_b32_e32 v223, v139
	v_mov_b32_e32 v242, v140
	v_mov_b32_e32 v243, v141
	v_mov_b32_e32 v244, v142
	v_mov_b32_e32 v245, v143
	v_mov_b32_e32 v199, v144
	v_mov_b32_e32 v206, v145
	v_mov_b32_e32 v207, v146
	v_mov_b32_e32 v226, v147
	s_add_i32 s48, s48, 1
	s_mov_b32 s65, 0
	v_readlane_b32 s2, v249, 0
	s_nop 0
	s_and_b32 s3, s2, 7
	s_lshr_b32 s2, s2, 3
	s_cmp_lt_u32 s2, 40
	s_cselect_b32 s38, 7, 6
	s_cmp_lt_u32 s48, s38
	s_cbranch_scc0 .Lg2_c1_extra
	s_lshl_b32 s20, s48, 6
	s_add_i32 s20, s20, s2
	s_cmp_ge_u32 s20, 0xd4
	s_cselect_b32 s21, 1, 0
	s_mul_i32 s60, s21, 0xd4
	s_sub_i32 s20, s20, s60
	s_lshr_b32 s61, s20, 2
	s_and_b32 s20, s20, 3
	s_lshl_b32 s21, s21, 3
	s_add_i32 s20, s20, s21
	s_lshl_b32 s20, s20, 3
	s_add_i32 s60, s20, s3
	s_add_i32 s64, s60, 32
	s_branch .Lg2_c1_have

.Lr2u_k:
	s_waitcnt vmcnt(0)
	s_barrier
	s_add_i32 m0, s36, 0xc000
	s_nop 0
	global_load_lds_dwordx4 v136, s[34:35]
	s_add_i32 m0, s36, 0xd000
	s_nop 0
	global_load_lds_dwordx4 v137, s[34:35]
	s_add_i32 m0, s36, 0xe000
	s_nop 0
	global_load_lds_dwordx4 v138, s[34:35]
	s_add_i32 m0, s36, 0xf000
	s_nop 0
	global_load_lds_dwordx4 v139, s[34:35]
	s_add_u32 s34, s34, 0x80
	s_addc_u32 s35, s35, 0
	ds_read_b128 v[148:151], v140 offset:0
	ds_read_b128 v[152:155], v140 offset:2048
	ds_read_b128 v[156:159], v140 offset:4096
	ds_read_b128 v[160:163], v140 offset:6144
	ds_read_b128 v[164:167], v140 offset:16384
	ds_read_b128 v[168:171], v140 offset:18432
	ds_read_b128 v[174:177], v140 offset:20480
	ds_read_b128 v[182:185], v140 offset:22528
	ds_read_b128 v[188:191], v142 offset:32768
	ds_read_b128 v[192:195], v142 offset:34816
	ds_read_b128 v[208:211], v142 offset:36864
	ds_read_b128 v[212:215], v142 offset:38912
	s_waitcnt lgkmcnt(0)
	s_setprio 3
	v_mfma_f32_16x16x32_bf16 v[62:65], v[188:191], v[148:151], v[62:65]
	v_mfma_f32_16x16x32_bf16 v[58:61], v[192:195], v[148:151], v[58:61]
	v_mfma_f32_16x16x32_bf16 v[54:57], v[208:211], v[148:151], v[54:57]
	v_mfma_f32_16x16x32_bf16 v[50:53], v[212:215], v[148:151], v[50:53]
	v_mfma_f32_16x16x32_bf16 v[46:49], v[188:191], v[152:155], v[46:49]
	v_mfma_f32_16x16x32_bf16 v[42:45], v[192:195], v[152:155], v[42:45]
	v_mfma_f32_16x16x32_bf16 v[38:41], v[208:211], v[152:155], v[38:41]
	v_mfma_f32_16x16x32_bf16 v[34:37], v[212:215], v[152:155], v[34:37]
	v_mfma_f32_16x16x32_bf16 v[30:33], v[188:191], v[156:159], v[30:33]
	v_mfma_f32_16x16x32_bf16 v[26:29], v[192:195], v[156:159], v[26:29]
	v_mfma_f32_16x16x32_bf16 v[22:25], v[208:211], v[156:159], v[22:25]
	v_mfma_f32_16x16x32_bf16 v[18:21], v[212:215], v[156:159], v[18:21]
	v_mfma_f32_16x16x32_bf16 v[14:17], v[188:191], v[160:163], v[14:17]
	v_mfma_f32_16x16x32_bf16 v[10:13], v[192:195], v[160:163], v[10:13]
	v_mfma_f32_16x16x32_bf16 v[6:9], v[208:211], v[160:163], v[6:9]
	v_mfma_f32_16x16x32_bf16 v[2:5], v[212:215], v[160:163], v[2:5]
	v_mfma_f32_16x16x32_bf16 v[66:69], v[188:191], v[164:167], v[66:69]
	v_mfma_f32_16x16x32_bf16 v[70:73], v[192:195], v[164:167], v[70:73]
	v_mfma_f32_16x16x32_bf16 v[74:77], v[208:211], v[164:167], v[74:77]
	v_mfma_f32_16x16x32_bf16 v[78:81], v[212:215], v[164:167], v[78:81]
	v_mfma_f32_16x16x32_bf16 v[82:85], v[188:191], v[168:171], v[82:85]
	v_mfma_f32_16x16x32_bf16 v[86:89], v[192:195], v[168:171], v[86:89]
	v_mfma_f32_16x16x32_bf16 v[90:93], v[208:211], v[168:171], v[90:93]
	v_mfma_f32_16x16x32_bf16 v[94:97], v[212:215], v[168:171], v[94:97]
	v_mfma_f32_16x16x32_bf16 v[98:101], v[188:191], v[174:177], v[98:101]
	v_mfma_f32_16x16x32_bf16 v[102:105], v[192:195], v[174:177], v[102:105]
	v_mfma_f32_16x16x32_bf16 v[106:109], v[208:211], v[174:177], v[106:109]
	v_mfma_f32_16x16x32_bf16 v[110:113], v[212:215], v[174:177], v[110:113]
	v_mfma_f32_16x16x32_bf16 v[114:117], v[188:191], v[182:185], v[114:117]
	v_mfma_f32_16x16x32_bf16 v[118:121], v[192:195], v[182:185], v[118:121]
	v_mfma_f32_16x16x32_bf16 v[122:125], v[208:211], v[182:185], v[122:125]
	v_mfma_f32_16x16x32_bf16 v[126:129], v[212:215], v[182:185], v[126:129]
	s_setprio 0
	ds_read_b128 v[148:151], v141 offset:0
	ds_read_b128 v[152:155], v141 offset:2048
	ds_read_b128 v[156:159], v141 offset:4096
	ds_read_b128 v[160:163], v141 offset:6144
	ds_read_b128 v[164:167], v141 offset:16384
	ds_read_b128 v[168:171], v141 offset:18432
	ds_read_b128 v[174:177], v141 offset:20480
	ds_read_b128 v[182:185], v141 offset:22528
	ds_read_b128 v[188:191], v143 offset:32768
	ds_read_b128 v[192:195], v143 offset:34816
	ds_read_b128 v[208:211], v143 offset:36864
	ds_read_b128 v[212:215], v143 offset:38912
	s_waitcnt lgkmcnt(0)
	s_barrier
	s_add_i32 m0, s36, 0x0
	s_nop 0
	global_load_lds_dwordx4 v136, s[30:31]
	s_add_i32 m0, s36, 0x1000
	s_nop 0
	global_load_lds_dwordx4 v137, s[30:31]
	s_add_i32 m0, s36, 0x2000
	s_nop 0
	global_load_lds_dwordx4 v138, s[30:31]
	s_add_i32 m0, s36, 0x3000
	s_nop 0
	global_load_lds_dwordx4 v139, s[30:31]
	s_add_i32 m0, s36, 0x4000
	s_nop 0
	global_load_lds_dwordx4 v136, s[44:45]
	s_add_i32 m0, s36, 0x5000
	s_nop 0
	global_load_lds_dwordx4 v137, s[44:45]
	s_add_i32 m0, s36, 0x6000
	s_nop 0
	global_load_lds_dwordx4 v138, s[44:45]
	s_add_i32 m0, s36, 0x7000
	s_nop 0
	global_load_lds_dwordx4 v139, s[44:45]
	s_add_u32 s30, s30, 0x80
	s_addc_u32 s31, s31, 0
	s_add_u32 s44, s44, 0x80
	s_addc_u32 s45, s45, 0
	s_setprio 3
	v_mfma_f32_16x16x32_bf16 v[62:65], v[188:191], v[148:151], v[62:65]
	v_mfma_f32_16x16x32_bf16 v[58:61], v[192:195], v[148:151], v[58:61]
	v_mfma_f32_16x16x32_bf16 v[54:57], v[208:211], v[148:151], v[54:57]
	v_mfma_f32_16x16x32_bf16 v[50:53], v[212:215], v[148:151], v[50:53]
	v_mfma_f32_16x16x32_bf16 v[46:49], v[188:191], v[152:155], v[46:49]
	v_mfma_f32_16x16x32_bf16 v[42:45], v[192:195], v[152:155], v[42:45]
	v_mfma_f32_16x16x32_bf16 v[38:41], v[208:211], v[152:155], v[38:41]
	v_mfma_f32_16x16x32_bf16 v[34:37], v[212:215], v[152:155], v[34:37]
	v_mfma_f32_16x16x32_bf16 v[30:33], v[188:191], v[156:159], v[30:33]
	v_mfma_f32_16x16x32_bf16 v[26:29], v[192:195], v[156:159], v[26:29]
	v_mfma_f32_16x16x32_bf16 v[22:25], v[208:211], v[156:159], v[22:25]
	v_mfma_f32_16x16x32_bf16 v[18:21], v[212:215], v[156:159], v[18:21]
	v_mfma_f32_16x16x32_bf16 v[14:17], v[188:191], v[160:163], v[14:17]
	v_mfma_f32_16x16x32_bf16 v[10:13], v[192:195], v[160:163], v[10:13]
	v_mfma_f32_16x16x32_bf16 v[6:9], v[208:211], v[160:163], v[6:9]
	v_mfma_f32_16x16x32_bf16 v[2:5], v[212:215], v[160:163], v[2:5]
	v_mfma_f32_16x16x32_bf16 v[66:69], v[188:191], v[164:167], v[66:69]
	v_mfma_f32_16x16x32_bf16 v[70:73], v[192:195], v[164:167], v[70:73]
	v_mfma_f32_16x16x32_bf16 v[74:77], v[208:211], v[164:167], v[74:77]
	v_mfma_f32_16x16x32_bf16 v[78:81], v[212:215], v[164:167], v[78:81]
	v_mfma_f32_16x16x32_bf16 v[82:85], v[188:191], v[168:171], v[82:85]
	v_mfma_f32_16x16x32_bf16 v[86:89], v[192:195], v[168:171], v[86:89]
	v_mfma_f32_16x16x32_bf16 v[90:93], v[208:211], v[168:171], v[90:93]
	v_mfma_f32_16x16x32_bf16 v[94:97], v[212:215], v[168:171], v[94:97]
	v_mfma_f32_16x16x32_bf16 v[98:101], v[188:191], v[174:177], v[98:101]
	v_mfma_f32_16x16x32_bf16 v[102:105], v[192:195], v[174:177], v[102:105]
	v_mfma_f32_16x16x32_bf16 v[106:109], v[208:211], v[174:177], v[106:109]
	v_mfma_f32_16x16x32_bf16 v[110:113], v[212:215], v[174:177], v[110:113]
	v_mfma_f32_16x16x32_bf16 v[114:117], v[188:191], v[182:185], v[114:117]
	v_mfma_f32_16x16x32_bf16 v[118:121], v[192:195], v[182:185], v[118:121]
	v_mfma_f32_16x16x32_bf16 v[122:125], v[208:211], v[182:185], v[122:125]
	v_mfma_f32_16x16x32_bf16 v[126:129], v[212:215], v[182:185], v[126:129]
	s_setprio 0
	s_waitcnt vmcnt(0)
	s_barrier
	s_add_i32 m0, s36, 0x8000
	s_nop 0
	global_load_lds_dwordx4 v136, s[34:35]
	s_add_i32 m0, s36, 0x9000
	s_nop 0
	global_load_lds_dwordx4 v137, s[34:35]
	s_add_i32 m0, s36, 0xa000
	s_nop 0
	global_load_lds_dwordx4 v138, s[34:35]
	s_add_i32 m0, s36, 0xb000
	s_nop 0
	global_load_lds_dwordx4 v139, s[34:35]
	s_add_u32 s34, s34, 0x80
	s_addc_u32 s35, s35, 0
	ds_read_b128 v[148:151], v140 offset:0
	ds_read_b128 v[152:155], v140 offset:2048
	ds_read_b128 v[156:159], v140 offset:4096
	ds_read_b128 v[160:163], v140 offset:6144
	ds_read_b128 v[164:167], v140 offset:16384
	ds_read_b128 v[168:171], v140 offset:18432
	ds_read_b128 v[174:177], v140 offset:20480
	ds_read_b128 v[182:185], v140 offset:22528
	ds_read_b128 v[188:191], v142 offset:49152
	ds_read_b128 v[192:195], v142 offset:51200
	ds_read_b128 v[208:211], v142 offset:53248
	ds_read_b128 v[212:215], v142 offset:55296
	s_waitcnt lgkmcnt(0)
	s_setprio 3
	v_mfma_f32_16x16x32_bf16 v[62:65], v[188:191], v[148:151], v[62:65]
	v_mfma_f32_16x16x32_bf16 v[58:61], v[192:195], v[148:151], v[58:61]
	v_mfma_f32_16x16x32_bf16 v[54:57], v[208:211], v[148:151], v[54:57]
	v_mfma_f32_16x16x32_bf16 v[50:53], v[212:215], v[148:151], v[50:53]
	v_mfma_f32_16x16x32_bf16 v[46:49], v[188:191], v[152:155], v[46:49]
	v_mfma_f32_16x16x32_bf16 v[42:45], v[192:195], v[152:155], v[42:45]
	v_mfma_f32_16x16x32_bf16 v[38:41], v[208:211], v[152:155], v[38:41]
	v_mfma_f32_16x16x32_bf16 v[34:37], v[212:215], v[152:155], v[34:37]
	v_mfma_f32_16x16x32_bf16 v[30:33], v[188:191], v[156:159], v[30:33]
	v_mfma_f32_16x16x32_bf16 v[26:29], v[192:195], v[156:159], v[26:29]
	v_mfma_f32_16x16x32_bf16 v[22:25], v[208:211], v[156:159], v[22:25]
	v_mfma_f32_16x16x32_bf16 v[18:21], v[212:215], v[156:159], v[18:21]
	v_mfma_f32_16x16x32_bf16 v[14:17], v[188:191], v[160:163], v[14:17]
	v_mfma_f32_16x16x32_bf16 v[10:13], v[192:195], v[160:163], v[10:13]
	v_mfma_f32_16x16x32_bf16 v[6:9], v[208:211], v[160:163], v[6:9]
	v_mfma_f32_16x16x32_bf16 v[2:5], v[212:215], v[160:163], v[2:5]
	v_mfma_f32_16x16x32_bf16 v[66:69], v[188:191], v[164:167], v[66:69]
	v_mfma_f32_16x16x32_bf16 v[70:73], v[192:195], v[164:167], v[70:73]
	v_mfma_f32_16x16x32_bf16 v[74:77], v[208:211], v[164:167], v[74:77]
	v_mfma_f32_16x16x32_bf16 v[78:81], v[212:215], v[164:167], v[78:81]
	v_mfma_f32_16x16x32_bf16 v[82:85], v[188:191], v[168:171], v[82:85]
	v_mfma_f32_16x16x32_bf16 v[86:89], v[192:195], v[168:171], v[86:89]
	v_mfma_f32_16x16x32_bf16 v[90:93], v[208:211], v[168:171], v[90:93]
	v_mfma_f32_16x16x32_bf16 v[94:97], v[212:215], v[168:171], v[94:97]
	v_mfma_f32_16x16x32_bf16 v[98:101], v[188:191], v[174:177], v[98:101]
	v_mfma_f32_16x16x32_bf16 v[102:105], v[192:195], v[174:177], v[102:105]
	v_mfma_f32_16x16x32_bf16 v[106:109], v[208:211], v[174:177], v[106:109]
	v_mfma_f32_16x16x32_bf16 v[110:113], v[212:215], v[174:177], v[110:113]
	v_mfma_f32_16x16x32_bf16 v[114:117], v[188:191], v[182:185], v[114:117]
	v_mfma_f32_16x16x32_bf16 v[118:121], v[192:195], v[182:185], v[118:121]
	v_mfma_f32_16x16x32_bf16 v[122:125], v[208:211], v[182:185], v[122:125]
	v_mfma_f32_16x16x32_bf16 v[126:129], v[212:215], v[182:185], v[126:129]
	s_setprio 0
	ds_read_b128 v[148:151], v141 offset:0
	ds_read_b128 v[152:155], v141 offset:2048
	ds_read_b128 v[156:159], v141 offset:4096
	ds_read_b128 v[160:163], v141 offset:6144
	ds_read_b128 v[164:167], v141 offset:16384
	ds_read_b128 v[168:171], v141 offset:18432
	ds_read_b128 v[174:177], v141 offset:20480
	ds_read_b128 v[182:185], v141 offset:22528
	ds_read_b128 v[188:191], v143 offset:49152
	ds_read_b128 v[192:195], v143 offset:51200
	ds_read_b128 v[208:211], v143 offset:53248
	ds_read_b128 v[212:215], v143 offset:55296
	s_waitcnt lgkmcnt(0)
	s_barrier
	s_add_i32 m0, s36, 0x0
	s_nop 0
	global_load_lds_dwordx4 v136, s[30:31]
	s_add_i32 m0, s36, 0x1000
	s_nop 0
	global_load_lds_dwordx4 v137, s[30:31]
	s_add_i32 m0, s36, 0x2000
	s_nop 0
	global_load_lds_dwordx4 v138, s[30:31]
	s_add_i32 m0, s36, 0x3000
	s_nop 0
	global_load_lds_dwordx4 v139, s[30:31]
	s_add_i32 m0, s36, 0x4000
	s_nop 0
	global_load_lds_dwordx4 v136, s[44:45]
	s_add_i32 m0, s36, 0x5000
	s_nop 0
	global_load_lds_dwordx4 v137, s[44:45]
	s_add_i32 m0, s36, 0x6000
	s_nop 0
	global_load_lds_dwordx4 v138, s[44:45]
	s_add_i32 m0, s36, 0x7000
	s_nop 0
	global_load_lds_dwordx4 v139, s[44:45]
	s_add_u32 s30, s30, 0x80
	s_addc_u32 s31, s31, 0
	s_add_u32 s44, s44, 0x80
	s_addc_u32 s45, s45, 0
	s_setprio 3
	v_mfma_f32_16x16x32_bf16 v[62:65], v[188:191], v[148:151], v[62:65]
	v_mfma_f32_16x16x32_bf16 v[58:61], v[192:195], v[148:151], v[58:61]
	v_mfma_f32_16x16x32_bf16 v[54:57], v[208:211], v[148:151], v[54:57]
	v_mfma_f32_16x16x32_bf16 v[50:53], v[212:215], v[148:151], v[50:53]
	v_mfma_f32_16x16x32_bf16 v[46:49], v[188:191], v[152:155], v[46:49]
	v_mfma_f32_16x16x32_bf16 v[42:45], v[192:195], v[152:155], v[42:45]
	v_mfma_f32_16x16x32_bf16 v[38:41], v[208:211], v[152:155], v[38:41]
	v_mfma_f32_16x16x32_bf16 v[34:37], v[212:215], v[152:155], v[34:37]
	v_mfma_f32_16x16x32_bf16 v[30:33], v[188:191], v[156:159], v[30:33]
	v_mfma_f32_16x16x32_bf16 v[26:29], v[192:195], v[156:159], v[26:29]
	v_mfma_f32_16x16x32_bf16 v[22:25], v[208:211], v[156:159], v[22:25]
	v_mfma_f32_16x16x32_bf16 v[18:21], v[212:215], v[156:159], v[18:21]
	v_mfma_f32_16x16x32_bf16 v[14:17], v[188:191], v[160:163], v[14:17]
	v_mfma_f32_16x16x32_bf16 v[10:13], v[192:195], v[160:163], v[10:13]
	v_mfma_f32_16x16x32_bf16 v[6:9], v[208:211], v[160:163], v[6:9]
	v_mfma_f32_16x16x32_bf16 v[2:5], v[212:215], v[160:163], v[2:5]
	v_mfma_f32_16x16x32_bf16 v[66:69], v[188:191], v[164:167], v[66:69]
	v_mfma_f32_16x16x32_bf16 v[70:73], v[192:195], v[164:167], v[70:73]
	v_mfma_f32_16x16x32_bf16 v[74:77], v[208:211], v[164:167], v[74:77]
	v_mfma_f32_16x16x32_bf16 v[78:81], v[212:215], v[164:167], v[78:81]
	v_mfma_f32_16x16x32_bf16 v[82:85], v[188:191], v[168:171], v[82:85]
	v_mfma_f32_16x16x32_bf16 v[86:89], v[192:195], v[168:171], v[86:89]
	v_mfma_f32_16x16x32_bf16 v[90:93], v[208:211], v[168:171], v[90:93]
	v_mfma_f32_16x16x32_bf16 v[94:97], v[212:215], v[168:171], v[94:97]
	v_mfma_f32_16x16x32_bf16 v[98:101], v[188:191], v[174:177], v[98:101]
	v_mfma_f32_16x16x32_bf16 v[102:105], v[192:195], v[174:177], v[102:105]
	v_mfma_f32_16x16x32_bf16 v[106:109], v[208:211], v[174:177], v[106:109]
	v_mfma_f32_16x16x32_bf16 v[110:113], v[212:215], v[174:177], v[110:113]
	v_mfma_f32_16x16x32_bf16 v[114:117], v[188:191], v[182:185], v[114:117]
	v_mfma_f32_16x16x32_bf16 v[118:121], v[192:195], v[182:185], v[118:121]
	v_mfma_f32_16x16x32_bf16 v[122:125], v[208:211], v[182:185], v[122:125]
	v_mfma_f32_16x16x32_bf16 v[126:129], v[212:215], v[182:185], v[126:129]
	s_setprio 0
	s_add_i32 s37, s37, -1
	s_cmp_lg_u32 s37, 0
	s_cbranch_scc1 .Lr2u_k
	s_waitcnt vmcnt(0)
	s_barrier
	s_add_i32 m0, s36, 0xc000
	s_nop 0
	global_load_lds_dwordx4 v136, s[34:35]
	s_add_i32 m0, s36, 0xd000
	s_nop 0
	global_load_lds_dwordx4 v137, s[34:35]
	s_add_i32 m0, s36, 0xe000
	s_nop 0
	global_load_lds_dwordx4 v138, s[34:35]
	s_add_i32 m0, s36, 0xf000
	s_nop 0
	global_load_lds_dwordx4 v139, s[34:35]
	s_add_u32 s34, s34, 0x80
	s_addc_u32 s35, s35, 0
	ds_read_b128 v[148:151], v140 offset:0
	ds_read_b128 v[152:155], v140 offset:2048
	ds_read_b128 v[156:159], v140 offset:4096
	ds_read_b128 v[160:163], v140 offset:6144
	ds_read_b128 v[164:167], v140 offset:16384
	ds_read_b128 v[168:171], v140 offset:18432
	ds_read_b128 v[174:177], v140 offset:20480
	ds_read_b128 v[182:185], v140 offset:22528
	ds_read_b128 v[188:191], v142 offset:32768
	ds_read_b128 v[192:195], v142 offset:34816
	ds_read_b128 v[208:211], v142 offset:36864
	ds_read_b128 v[212:215], v142 offset:38912
	s_waitcnt lgkmcnt(0)
	s_setprio 3
	v_mfma_f32_16x16x32_bf16 v[62:65], v[188:191], v[148:151], v[62:65]
	v_mfma_f32_16x16x32_bf16 v[58:61], v[192:195], v[148:151], v[58:61]
	v_mfma_f32_16x16x32_bf16 v[54:57], v[208:211], v[148:151], v[54:57]
	v_mfma_f32_16x16x32_bf16 v[50:53], v[212:215], v[148:151], v[50:53]
	v_mfma_f32_16x16x32_bf16 v[46:49], v[188:191], v[152:155], v[46:49]
	v_mfma_f32_16x16x32_bf16 v[42:45], v[192:195], v[152:155], v[42:45]
	v_mfma_f32_16x16x32_bf16 v[38:41], v[208:211], v[152:155], v[38:41]
	v_mfma_f32_16x16x32_bf16 v[34:37], v[212:215], v[152:155], v[34:37]
	v_mfma_f32_16x16x32_bf16 v[30:33], v[188:191], v[156:159], v[30:33]
	v_mfma_f32_16x16x32_bf16 v[26:29], v[192:195], v[156:159], v[26:29]
	v_mfma_f32_16x16x32_bf16 v[22:25], v[208:211], v[156:159], v[22:25]
	v_mfma_f32_16x16x32_bf16 v[18:21], v[212:215], v[156:159], v[18:21]
	v_mfma_f32_16x16x32_bf16 v[14:17], v[188:191], v[160:163], v[14:17]
	v_mfma_f32_16x16x32_bf16 v[10:13], v[192:195], v[160:163], v[10:13]
	v_mfma_f32_16x16x32_bf16 v[6:9], v[208:211], v[160:163], v[6:9]
	v_mfma_f32_16x16x32_bf16 v[2:5], v[212:215], v[160:163], v[2:5]
	v_mfma_f32_16x16x32_bf16 v[66:69], v[188:191], v[164:167], v[66:69]
	v_mfma_f32_16x16x32_bf16 v[70:73], v[192:195], v[164:167], v[70:73]
	v_mfma_f32_16x16x32_bf16 v[74:77], v[208:211], v[164:167], v[74:77]
	v_mfma_f32_16x16x32_bf16 v[78:81], v[212:215], v[164:167], v[78:81]
	v_mfma_f32_16x16x32_bf16 v[82:85], v[188:191], v[168:171], v[82:85]
	v_mfma_f32_16x16x32_bf16 v[86:89], v[192:195], v[168:171], v[86:89]
	v_mfma_f32_16x16x32_bf16 v[90:93], v[208:211], v[168:171], v[90:93]
	v_mfma_f32_16x16x32_bf16 v[94:97], v[212:215], v[168:171], v[94:97]
	v_mfma_f32_16x16x32_bf16 v[98:101], v[188:191], v[174:177], v[98:101]
	v_mfma_f32_16x16x32_bf16 v[102:105], v[192:195], v[174:177], v[102:105]
	v_mfma_f32_16x16x32_bf16 v[106:109], v[208:211], v[174:177], v[106:109]
	v_mfma_f32_16x16x32_bf16 v[110:113], v[212:215], v[174:177], v[110:113]
	v_mfma_f32_16x16x32_bf16 v[114:117], v[188:191], v[182:185], v[114:117]
	v_mfma_f32_16x16x32_bf16 v[118:121], v[192:195], v[182:185], v[118:121]
	v_mfma_f32_16x16x32_bf16 v[122:125], v[208:211], v[182:185], v[122:125]
	v_mfma_f32_16x16x32_bf16 v[126:129], v[212:215], v[182:185], v[126:129]
	s_setprio 0
	ds_read_b128 v[148:151], v141 offset:0
	ds_read_b128 v[152:155], v141 offset:2048
	ds_read_b128 v[156:159], v141 offset:4096
	ds_read_b128 v[160:163], v141 offset:6144
	ds_read_b128 v[164:167], v141 offset:16384
	ds_read_b128 v[168:171], v141 offset:18432
	ds_read_b128 v[174:177], v141 offset:20480
	ds_read_b128 v[182:185], v141 offset:22528
	ds_read_b128 v[188:191], v143 offset:32768
	ds_read_b128 v[192:195], v143 offset:34816
	ds_read_b128 v[208:211], v143 offset:36864
	ds_read_b128 v[212:215], v143 offset:38912
	s_waitcnt lgkmcnt(0)
	s_barrier
	s_add_i32 m0, s36, 0x0
	s_nop 0
	global_load_lds_dwordx4 v136, s[30:31]
	s_add_i32 m0, s36, 0x1000
	s_nop 0
	global_load_lds_dwordx4 v137, s[30:31]
	s_add_i32 m0, s36, 0x2000
	s_nop 0
	global_load_lds_dwordx4 v138, s[30:31]
	s_add_i32 m0, s36, 0x3000
	s_nop 0
	global_load_lds_dwordx4 v139, s[30:31]
	s_add_i32 m0, s36, 0x4000
	s_nop 0
	global_load_lds_dwordx4 v136, s[44:45]
	s_add_i32 m0, s36, 0x5000
	s_nop 0
	global_load_lds_dwordx4 v137, s[44:45]
	s_add_i32 m0, s36, 0x6000
	s_nop 0
	global_load_lds_dwordx4 v138, s[44:45]
	s_add_i32 m0, s36, 0x7000
	s_nop 0
	global_load_lds_dwordx4 v139, s[44:45]
	s_add_u32 s30, s30, 0x80
	s_addc_u32 s31, s31, 0
	s_add_u32 s44, s44, 0x80
	s_addc_u32 s45, s45, 0
	s_setprio 3
	v_mfma_f32_16x16x32_bf16 v[62:65], v[188:191], v[148:151], v[62:65]
	v_mfma_f32_16x16x32_bf16 v[58:61], v[192:195], v[148:151], v[58:61]
	v_mfma_f32_16x16x32_bf16 v[54:57], v[208:211], v[148:151], v[54:57]
	v_mfma_f32_16x16x32_bf16 v[50:53], v[212:215], v[148:151], v[50:53]
	v_mfma_f32_16x16x32_bf16 v[46:49], v[188:191], v[152:155], v[46:49]
	v_mfma_f32_16x16x32_bf16 v[42:45], v[192:195], v[152:155], v[42:45]
	v_mfma_f32_16x16x32_bf16 v[38:41], v[208:211], v[152:155], v[38:41]
	v_mfma_f32_16x16x32_bf16 v[34:37], v[212:215], v[152:155], v[34:37]
	v_mfma_f32_16x16x32_bf16 v[30:33], v[188:191], v[156:159], v[30:33]
	v_mfma_f32_16x16x32_bf16 v[26:29], v[192:195], v[156:159], v[26:29]
	v_mfma_f32_16x16x32_bf16 v[22:25], v[208:211], v[156:159], v[22:25]
	v_mfma_f32_16x16x32_bf16 v[18:21], v[212:215], v[156:159], v[18:21]
	v_mfma_f32_16x16x32_bf16 v[14:17], v[188:191], v[160:163], v[14:17]
	v_mfma_f32_16x16x32_bf16 v[10:13], v[192:195], v[160:163], v[10:13]
	v_mfma_f32_16x16x32_bf16 v[6:9], v[208:211], v[160:163], v[6:9]
	v_mfma_f32_16x16x32_bf16 v[2:5], v[212:215], v[160:163], v[2:5]
	v_mfma_f32_16x16x32_bf16 v[66:69], v[188:191], v[164:167], v[66:69]
	v_mfma_f32_16x16x32_bf16 v[70:73], v[192:195], v[164:167], v[70:73]
	v_mfma_f32_16x16x32_bf16 v[74:77], v[208:211], v[164:167], v[74:77]
	v_mfma_f32_16x16x32_bf16 v[78:81], v[212:215], v[164:167], v[78:81]
	v_mfma_f32_16x16x32_bf16 v[82:85], v[188:191], v[168:171], v[82:85]
	v_mfma_f32_16x16x32_bf16 v[86:89], v[192:195], v[168:171], v[86:89]
	v_mfma_f32_16x16x32_bf16 v[90:93], v[208:211], v[168:171], v[90:93]
	v_mfma_f32_16x16x32_bf16 v[94:97], v[212:215], v[168:171], v[94:97]
	v_mfma_f32_16x16x32_bf16 v[98:101], v[188:191], v[174:177], v[98:101]
	v_mfma_f32_16x16x32_bf16 v[102:105], v[192:195], v[174:177], v[102:105]
	v_mfma_f32_16x16x32_bf16 v[106:109], v[208:211], v[174:177], v[106:109]
	v_mfma_f32_16x16x32_bf16 v[110:113], v[212:215], v[174:177], v[110:113]
	v_mfma_f32_16x16x32_bf16 v[114:117], v[188:191], v[182:185], v[114:117]
	v_mfma_f32_16x16x32_bf16 v[118:121], v[192:195], v[182:185], v[118:121]
	v_mfma_f32_16x16x32_bf16 v[122:125], v[208:211], v[182:185], v[122:125]
	v_mfma_f32_16x16x32_bf16 v[126:129], v[212:215], v[182:185], v[126:129]
	s_setprio 0
	s_waitcnt vmcnt(0)
	s_barrier
	ds_read_b128 v[148:151], v140 offset:0
	ds_read_b128 v[152:155], v140 offset:2048
	ds_read_b128 v[156:159], v140 offset:4096
	ds_read_b128 v[160:163], v140 offset:6144
	ds_read_b128 v[164:167], v140 offset:16384
	ds_read_b128 v[168:171], v140 offset:18432
	ds_read_b128 v[174:177], v140 offset:20480
	ds_read_b128 v[182:185], v140 offset:22528
	ds_read_b128 v[188:191], v142 offset:49152
	ds_read_b128 v[192:195], v142 offset:51200
	ds_read_b128 v[208:211], v142 offset:53248
	ds_read_b128 v[212:215], v142 offset:55296
	s_waitcnt lgkmcnt(0)
	s_setprio 3
	v_mfma_f32_16x16x32_bf16 v[62:65], v[188:191], v[148:151], v[62:65]
	v_mfma_f32_16x16x32_bf16 v[58:61], v[192:195], v[148:151], v[58:61]
	v_mfma_f32_16x16x32_bf16 v[54:57], v[208:211], v[148:151], v[54:57]
	v_mfma_f32_16x16x32_bf16 v[50:53], v[212:215], v[148:151], v[50:53]
	v_mfma_f32_16x16x32_bf16 v[46:49], v[188:191], v[152:155], v[46:49]
	v_mfma_f32_16x16x32_bf16 v[42:45], v[192:195], v[152:155], v[42:45]
	v_mfma_f32_16x16x32_bf16 v[38:41], v[208:211], v[152:155], v[38:41]
	v_mfma_f32_16x16x32_bf16 v[34:37], v[212:215], v[152:155], v[34:37]
	v_mfma_f32_16x16x32_bf16 v[30:33], v[188:191], v[156:159], v[30:33]
	v_mfma_f32_16x16x32_bf16 v[26:29], v[192:195], v[156:159], v[26:29]
	v_mfma_f32_16x16x32_bf16 v[22:25], v[208:211], v[156:159], v[22:25]
	v_mfma_f32_16x16x32_bf16 v[18:21], v[212:215], v[156:159], v[18:21]
	v_mfma_f32_16x16x32_bf16 v[14:17], v[188:191], v[160:163], v[14:17]
	v_mfma_f32_16x16x32_bf16 v[10:13], v[192:195], v[160:163], v[10:13]
	v_mfma_f32_16x16x32_bf16 v[6:9], v[208:211], v[160:163], v[6:9]
	v_mfma_f32_16x16x32_bf16 v[2:5], v[212:215], v[160:163], v[2:5]
	v_mfma_f32_16x16x32_bf16 v[66:69], v[188:191], v[164:167], v[66:69]
	v_mfma_f32_16x16x32_bf16 v[70:73], v[192:195], v[164:167], v[70:73]
	v_mfma_f32_16x16x32_bf16 v[74:77], v[208:211], v[164:167], v[74:77]
	v_mfma_f32_16x16x32_bf16 v[78:81], v[212:215], v[164:167], v[78:81]
	v_mfma_f32_16x16x32_bf16 v[82:85], v[188:191], v[168:171], v[82:85]
	v_mfma_f32_16x16x32_bf16 v[86:89], v[192:195], v[168:171], v[86:89]
	v_mfma_f32_16x16x32_bf16 v[90:93], v[208:211], v[168:171], v[90:93]
	v_mfma_f32_16x16x32_bf16 v[94:97], v[212:215], v[168:171], v[94:97]
	v_mfma_f32_16x16x32_bf16 v[98:101], v[188:191], v[174:177], v[98:101]
	v_mfma_f32_16x16x32_bf16 v[102:105], v[192:195], v[174:177], v[102:105]
	v_mfma_f32_16x16x32_bf16 v[106:109], v[208:211], v[174:177], v[106:109]
	v_mfma_f32_16x16x32_bf16 v[110:113], v[212:215], v[174:177], v[110:113]
	v_mfma_f32_16x16x32_bf16 v[114:117], v[188:191], v[182:185], v[114:117]
	v_mfma_f32_16x16x32_bf16 v[118:121], v[192:195], v[182:185], v[118:121]
	v_mfma_f32_16x16x32_bf16 v[122:125], v[208:211], v[182:185], v[122:125]
	v_mfma_f32_16x16x32_bf16 v[126:129], v[212:215], v[182:185], v[126:129]
	s_setprio 0
	ds_read_b128 v[148:151], v141 offset:0
	ds_read_b128 v[152:155], v141 offset:2048
	ds_read_b128 v[156:159], v141 offset:4096
	ds_read_b128 v[160:163], v141 offset:6144
	ds_read_b128 v[164:167], v141 offset:16384
	ds_read_b128 v[168:171], v141 offset:18432
	ds_read_b128 v[174:177], v141 offset:20480
	ds_read_b128 v[182:185], v141 offset:22528
	ds_read_b128 v[188:191], v143 offset:49152
	ds_read_b128 v[192:195], v143 offset:51200
	ds_read_b128 v[208:211], v143 offset:53248
	ds_read_b128 v[212:215], v143 offset:55296
	s_waitcnt lgkmcnt(0)
	s_setprio 3
	v_mfma_f32_16x16x32_bf16 v[62:65], v[188:191], v[148:151], v[62:65]
	v_mfma_f32_16x16x32_bf16 v[58:61], v[192:195], v[148:151], v[58:61]
	v_mfma_f32_16x16x32_bf16 v[54:57], v[208:211], v[148:151], v[54:57]
	v_mfma_f32_16x16x32_bf16 v[50:53], v[212:215], v[148:151], v[50:53]
	v_mfma_f32_16x16x32_bf16 v[46:49], v[188:191], v[152:155], v[46:49]
	v_mfma_f32_16x16x32_bf16 v[42:45], v[192:195], v[152:155], v[42:45]
	v_mfma_f32_16x16x32_bf16 v[38:41], v[208:211], v[152:155], v[38:41]
	v_mfma_f32_16x16x32_bf16 v[34:37], v[212:215], v[152:155], v[34:37]
	v_mfma_f32_16x16x32_bf16 v[30:33], v[188:191], v[156:159], v[30:33]
	v_mfma_f32_16x16x32_bf16 v[26:29], v[192:195], v[156:159], v[26:29]
	v_mfma_f32_16x16x32_bf16 v[22:25], v[208:211], v[156:159], v[22:25]
	v_mfma_f32_16x16x32_bf16 v[18:21], v[212:215], v[156:159], v[18:21]
	v_mfma_f32_16x16x32_bf16 v[14:17], v[188:191], v[160:163], v[14:17]
	v_mfma_f32_16x16x32_bf16 v[10:13], v[192:195], v[160:163], v[10:13]
	v_mfma_f32_16x16x32_bf16 v[6:9], v[208:211], v[160:163], v[6:9]
	v_mfma_f32_16x16x32_bf16 v[2:5], v[212:215], v[160:163], v[2:5]
	v_mfma_f32_16x16x32_bf16 v[66:69], v[188:191], v[164:167], v[66:69]
	v_mfma_f32_16x16x32_bf16 v[70:73], v[192:195], v[164:167], v[70:73]
	v_mfma_f32_16x16x32_bf16 v[74:77], v[208:211], v[164:167], v[74:77]
	v_mfma_f32_16x16x32_bf16 v[78:81], v[212:215], v[164:167], v[78:81]
	v_mfma_f32_16x16x32_bf16 v[82:85], v[188:191], v[168:171], v[82:85]
	v_mfma_f32_16x16x32_bf16 v[86:89], v[192:195], v[168:171], v[86:89]
	v_mfma_f32_16x16x32_bf16 v[90:93], v[208:211], v[168:171], v[90:93]
	v_mfma_f32_16x16x32_bf16 v[94:97], v[212:215], v[168:171], v[94:97]
	v_mfma_f32_16x16x32_bf16 v[98:101], v[188:191], v[174:177], v[98:101]
	v_mfma_f32_16x16x32_bf16 v[102:105], v[192:195], v[174:177], v[102:105]
	v_mfma_f32_16x16x32_bf16 v[106:109], v[208:211], v[174:177], v[106:109]
	v_mfma_f32_16x16x32_bf16 v[110:113], v[212:215], v[174:177], v[110:113]
	v_mfma_f32_16x16x32_bf16 v[114:117], v[188:191], v[182:185], v[114:117]
	v_mfma_f32_16x16x32_bf16 v[118:121], v[192:195], v[182:185], v[118:121]
	v_mfma_f32_16x16x32_bf16 v[122:125], v[208:211], v[182:185], v[122:125]
	v_mfma_f32_16x16x32_bf16 v[126:129], v[212:215], v[182:185], v[126:129]
	s_setprio 0
	v_lshrrev_b32_e32 v144, 7, v196
	v_and_b32_e32 v145, 15, v196
	v_lshl_or_b32 v144, v144, 6, v145
	v_lshlrev_b32_e32 v144, 12, v144
	v_bfe_u32 v145, v196, 6, 1
	v_bfe_u32 v146, v196, 4, 2
	v_lshlrev_b32_e32 v145, 8, v145
	v_lshl_or_b32 v145, v146, 4, v145
	v_add_u32_e32 v136, v144, v145
	v_add_u32_e32 v137, 0x10000, v136
	v_add_u32_e32 v138, 0x20000, v136
	v_add_u32_e32 v139, 0x30000, v136
	s_nop 7
	s_nop 7
	s_nop 7
	global_load_dwordx4 v[148:151], v136, s[50:51] offset:0
	global_load_dwordx4 v[152:155], v136, s[50:51] offset:64
	global_load_dwordx4 v[156:159], v136, s[50:51] offset:128
	global_load_dwordx4 v[160:163], v136, s[50:51] offset:192
	global_load_dwordx4 v[164:167], v137, s[50:51] offset:0
	global_load_dwordx4 v[168:171], v137, s[50:51] offset:64
	global_load_dwordx4 v[174:177], v137, s[50:51] offset:128
	global_load_dwordx4 v[182:185], v137, s[50:51] offset:192
	global_load_dwordx4 v[188:191], v138, s[50:51] offset:0
	global_load_dwordx4 v[192:195], v138, s[50:51] offset:64
	global_load_dwordx4 v[208:211], v138, s[50:51] offset:128
	global_load_dwordx4 v[212:215], v138, s[50:51] offset:192
	global_load_dwordx4 v[216:219], v139, s[50:51] offset:0
	global_load_dwordx4 v[220:223], v139, s[50:51] offset:64
	global_load_dwordx4 v[242:245], v139, s[50:51] offset:128
	global_load_dwordx4 v[144:147], v139, s[50:51] offset:192
	s_waitcnt vmcnt(0)
	v_pk_add_f32 v[62:63], v[62:63], v[148:149]
	v_pk_add_f32 v[64:65], v[64:65], v[150:151]
	v_pk_add_f32 v[58:59], v[58:59], v[152:153]
	v_pk_add_f32 v[60:61], v[60:61], v[154:155]
	v_pk_add_f32 v[54:55], v[54:55], v[156:157]
	v_pk_add_f32 v[56:57], v[56:57], v[158:159]
	v_pk_add_f32 v[50:51], v[50:51], v[160:161]
	v_pk_add_f32 v[52:53], v[52:53], v[162:163]
	v_pk_add_f32 v[46:47], v[46:47], v[164:165]
	v_pk_add_f32 v[48:49], v[48:49], v[166:167]
	v_pk_add_f32 v[42:43], v[42:43], v[168:169]
	v_pk_add_f32 v[44:45], v[44:45], v[170:171]
	v_pk_add_f32 v[38:39], v[38:39], v[174:175]
	v_pk_add_f32 v[40:41], v[40:41], v[176:177]
	v_pk_add_f32 v[34:35], v[34:35], v[182:183]
	v_pk_add_f32 v[36:37], v[36:37], v[184:185]
	v_pk_add_f32 v[30:31], v[30:31], v[188:189]
	v_pk_add_f32 v[32:33], v[32:33], v[190:191]
	v_pk_add_f32 v[26:27], v[26:27], v[192:193]
	v_pk_add_f32 v[28:29], v[28:29], v[194:195]
	v_pk_add_f32 v[22:23], v[22:23], v[208:209]
	v_pk_add_f32 v[24:25], v[24:25], v[210:211]
	v_pk_add_f32 v[18:19], v[18:19], v[212:213]
	v_pk_add_f32 v[20:21], v[20:21], v[214:215]
	v_pk_add_f32 v[14:15], v[14:15], v[216:217]
	v_pk_add_f32 v[16:17], v[16:17], v[218:219]
	v_pk_add_f32 v[10:11], v[10:11], v[220:221]
	v_pk_add_f32 v[12:13], v[12:13], v[222:223]
	v_pk_add_f32 v[6:7], v[6:7], v[242:243]
	v_pk_add_f32 v[8:9], v[8:9], v[244:245]
	v_pk_add_f32 v[2:3], v[2:3], v[144:145]
	v_pk_add_f32 v[4:5], v[4:5], v[146:147]
	global_load_dwordx4 v[148:151], v136, s[52:53] offset:0
	global_load_dwordx4 v[152:155], v136, s[52:53] offset:64
	global_load_dwordx4 v[156:159], v136, s[52:53] offset:128
	global_load_dwordx4 v[160:163], v136, s[52:53] offset:192
	global_load_dwordx4 v[164:167], v137, s[52:53] offset:0
	global_load_dwordx4 v[168:171], v137, s[52:53] offset:64
	global_load_dwordx4 v[174:177], v137, s[52:53] offset:128
	global_load_dwordx4 v[182:185], v137, s[52:53] offset:192
	global_load_dwordx4 v[188:191], v138, s[52:53] offset:0
	global_load_dwordx4 v[192:195], v138, s[52:53] offset:64
	global_load_dwordx4 v[208:211], v138, s[52:53] offset:128
	global_load_dwordx4 v[212:215], v138, s[52:53] offset:192
	global_load_dwordx4 v[216:219], v139, s[52:53] offset:0
	global_load_dwordx4 v[220:223], v139, s[52:53] offset:64
	global_load_dwordx4 v[242:245], v139, s[52:53] offset:128
	global_load_dwordx4 v[144:147], v139, s[52:53] offset:192
	global_store_dwordx4 v136, v[62:65], s[40:41] offset:0
	global_store_dwordx4 v136, v[58:61], s[40:41] offset:64
	global_store_dwordx4 v136, v[54:57], s[40:41] offset:128
	global_store_dwordx4 v136, v[50:53], s[40:41] offset:192
	global_store_dwordx4 v137, v[46:49], s[40:41] offset:0
	global_store_dwordx4 v137, v[42:45], s[40:41] offset:64
	global_store_dwordx4 v137, v[38:41], s[40:41] offset:128
	global_store_dwordx4 v137, v[34:37], s[40:41] offset:192
	global_store_dwordx4 v138, v[30:33], s[40:41] offset:0
	global_store_dwordx4 v138, v[26:29], s[40:41] offset:64
	global_store_dwordx4 v138, v[22:25], s[40:41] offset:128
	global_store_dwordx4 v138, v[18:21], s[40:41] offset:192
	global_store_dwordx4 v139, v[14:17], s[40:41] offset:0
	global_store_dwordx4 v139, v[10:13], s[40:41] offset:64
	global_store_dwordx4 v139, v[6:9], s[40:41] offset:128
	global_store_dwordx4 v139, v[2:5], s[40:41] offset:192
	s_waitcnt vmcnt(0)
	v_pk_add_f32 v[66:67], v[66:67], v[148:149]
	v_pk_add_f32 v[68:69], v[68:69], v[150:151]
	v_pk_add_f32 v[70:71], v[70:71], v[152:153]
	v_pk_add_f32 v[72:73], v[72:73], v[154:155]
	v_pk_add_f32 v[74:75], v[74:75], v[156:157]
	v_pk_add_f32 v[76:77], v[76:77], v[158:159]
	v_pk_add_f32 v[78:79], v[78:79], v[160:161]
	v_pk_add_f32 v[80:81], v[80:81], v[162:163]
	v_pk_add_f32 v[82:83], v[82:83], v[164:165]
	v_pk_add_f32 v[84:85], v[84:85], v[166:167]
	v_pk_add_f32 v[86:87], v[86:87], v[168:169]
	v_pk_add_f32 v[88:89], v[88:89], v[170:171]
	v_pk_add_f32 v[90:91], v[90:91], v[174:175]
	v_pk_add_f32 v[92:93], v[92:93], v[176:177]
	v_pk_add_f32 v[94:95], v[94:95], v[182:183]
	v_pk_add_f32 v[96:97], v[96:97], v[184:185]
	v_pk_add_f32 v[98:99], v[98:99], v[188:189]
	v_pk_add_f32 v[100:101], v[100:101], v[190:191]
	v_pk_add_f32 v[102:103], v[102:103], v[192:193]
	v_pk_add_f32 v[104:105], v[104:105], v[194:195]
	v_pk_add_f32 v[106:107], v[106:107], v[208:209]
	v_pk_add_f32 v[108:109], v[108:109], v[210:211]
	v_pk_add_f32 v[110:111], v[110:111], v[212:213]
	v_pk_add_f32 v[112:113], v[112:113], v[214:215]
	v_pk_add_f32 v[114:115], v[114:115], v[216:217]
	v_pk_add_f32 v[116:117], v[116:117], v[218:219]
	v_pk_add_f32 v[118:119], v[118:119], v[220:221]
	v_pk_add_f32 v[120:121], v[120:121], v[222:223]
	v_pk_add_f32 v[122:123], v[122:123], v[242:243]
	v_pk_add_f32 v[124:125], v[124:125], v[244:245]
	v_pk_add_f32 v[126:127], v[126:127], v[144:145]
	v_pk_add_f32 v[128:129], v[128:129], v[146:147]
	global_store_dwordx4 v136, v[66:69], s[42:43] offset:0
	global_store_dwordx4 v136, v[70:73], s[42:43] offset:64
	global_store_dwordx4 v136, v[74:77], s[42:43] offset:128
	global_store_dwordx4 v136, v[78:81], s[42:43] offset:192
	global_store_dwordx4 v137, v[82:85], s[42:43] offset:0
	global_store_dwordx4 v137, v[86:89], s[42:43] offset:64
	global_store_dwordx4 v137, v[90:93], s[42:43] offset:128
	global_store_dwordx4 v137, v[94:97], s[42:43] offset:192
	global_store_dwordx4 v138, v[98:101], s[42:43] offset:0
	global_store_dwordx4 v138, v[102:105], s[42:43] offset:64
	global_store_dwordx4 v138, v[106:109], s[42:43] offset:128
	global_store_dwordx4 v138, v[110:113], s[42:43] offset:192
	global_store_dwordx4 v139, v[114:117], s[42:43] offset:0
	global_store_dwordx4 v139, v[118:121], s[42:43] offset:64
	global_store_dwordx4 v139, v[122:125], s[42:43] offset:128
	global_store_dwordx4 v139, v[126:129], s[42:43] offset:192
	s_branch .LBB0_2211

.Lf2_k:
	s_waitcnt vmcnt(0)
	s_barrier
	s_add_i32 m0, s64, 0xc000
	s_nop 0
	global_load_lds_dwordx4 v76, s[58:59]
	s_add_i32 m0, s64, 0xd000
	s_nop 0
	global_load_lds_dwordx4 v77, s[58:59]
	s_add_i32 m0, s64, 0xe000
	s_nop 0
	global_load_lds_dwordx4 v78, s[58:59]
	s_add_i32 m0, s64, 0xf000
	s_nop 0
	global_load_lds_dwordx4 v79, s[58:59]
	s_add_u32 s58, s58, 0x80
	s_addc_u32 s59, s59, 0
	ds_read_b128 v[148:151], v80 offset:0
	ds_read_b128 v[152:155], v80 offset:2048
	ds_read_b128 v[156:159], v80 offset:4096
	ds_read_b128 v[160:163], v80 offset:6144
	ds_read_b128 v[188:191], v144 offset:32768
	ds_read_b128 v[192:195], v144 offset:34816
	ds_read_b128 v[208:211], v144 offset:36864
	ds_read_b128 v[212:215], v144 offset:38912
	ds_read_b128 v[164:167], v80 offset:16384
	ds_read_b128 v[168:171], v80 offset:18432
	ds_read_b128 v[174:177], v80 offset:20480
	ds_read_b128 v[182:185], v80 offset:22528
	s_setprio 3
	s_waitcnt lgkmcnt(4)
	v_mfma_f32_16x16x32_bf16 v[62:65], v[188:191], v[148:151], v[62:65]
	v_mfma_f32_16x16x32_bf16 v[54:57], v[192:195], v[148:151], v[54:57]
	v_mfma_f32_16x16x32_bf16 v[58:61], v[208:211], v[148:151], v[58:61]
	v_mfma_f32_16x16x32_bf16 v[50:53], v[212:215], v[148:151], v[50:53]
	v_mfma_f32_16x16x32_bf16 v[46:49], v[188:191], v[152:155], v[46:49]
	v_mfma_f32_16x16x32_bf16 v[38:41], v[192:195], v[152:155], v[38:41]
	v_mfma_f32_16x16x32_bf16 v[42:45], v[208:211], v[152:155], v[42:45]
	v_mfma_f32_16x16x32_bf16 v[34:37], v[212:215], v[152:155], v[34:37]
	v_mfma_f32_16x16x32_bf16 v[30:33], v[188:191], v[156:159], v[30:33]
	v_mfma_f32_16x16x32_bf16 v[22:25], v[192:195], v[156:159], v[22:25]
	v_mfma_f32_16x16x32_bf16 v[26:29], v[208:211], v[156:159], v[26:29]
	v_mfma_f32_16x16x32_bf16 v[18:21], v[212:215], v[156:159], v[18:21]
	v_mfma_f32_16x16x32_bf16 v[14:17], v[188:191], v[160:163], v[14:17]
	v_mfma_f32_16x16x32_bf16 v[6:9], v[192:195], v[160:163], v[6:9]
	v_mfma_f32_16x16x32_bf16 v[10:13], v[208:211], v[160:163], v[10:13]
	v_mfma_f32_16x16x32_bf16 v[2:5], v[212:215], v[160:163], v[2:5]
	s_waitcnt lgkmcnt(0)
	v_mfma_f32_16x16x32_bf16 v[66:69], v[188:191], v[164:167], v[66:69]
	v_mfma_f32_16x16x32_bf16 v[70:73], v[192:195], v[164:167], v[70:73]
	v_mfma_f32_16x16x32_bf16 v[82:85], v[208:211], v[164:167], v[82:85]
	v_mfma_f32_16x16x32_bf16 v[86:89], v[212:215], v[164:167], v[86:89]
	v_mfma_f32_16x16x32_bf16 v[90:93], v[188:191], v[168:171], v[90:93]
	v_mfma_f32_16x16x32_bf16 v[94:97], v[192:195], v[168:171], v[94:97]
	v_mfma_f32_16x16x32_bf16 v[98:101], v[208:211], v[168:171], v[98:101]
	v_mfma_f32_16x16x32_bf16 v[102:105], v[212:215], v[168:171], v[102:105]
	v_mfma_f32_16x16x32_bf16 v[106:109], v[188:191], v[174:177], v[106:109]
	v_mfma_f32_16x16x32_bf16 v[110:113], v[192:195], v[174:177], v[110:113]
	v_mfma_f32_16x16x32_bf16 v[114:117], v[208:211], v[174:177], v[114:117]
	v_mfma_f32_16x16x32_bf16 v[118:121], v[212:215], v[174:177], v[118:121]
	v_mfma_f32_16x16x32_bf16 v[122:125], v[188:191], v[182:185], v[122:125]
	v_mfma_f32_16x16x32_bf16 v[126:129], v[192:195], v[182:185], v[126:129]
	v_mfma_f32_16x16x32_bf16 v[136:139], v[208:211], v[182:185], v[136:139]
	v_mfma_f32_16x16x32_bf16 v[140:143], v[212:215], v[182:185], v[140:143]
	s_setprio 0
	ds_read_b128 v[148:151], v81 offset:0
	ds_read_b128 v[152:155], v81 offset:2048
	ds_read_b128 v[156:159], v81 offset:4096
	ds_read_b128 v[160:163], v81 offset:6144
	ds_read_b128 v[188:191], v145 offset:32768
	ds_read_b128 v[192:195], v145 offset:34816
	ds_read_b128 v[208:211], v145 offset:36864
	ds_read_b128 v[212:215], v145 offset:38912
	ds_read_b128 v[164:167], v81 offset:16384
	ds_read_b128 v[168:171], v81 offset:18432
	ds_read_b128 v[174:177], v81 offset:20480
	ds_read_b128 v[182:185], v81 offset:22528
	s_waitcnt lgkmcnt(0)
	s_barrier
	s_add_i32 m0, s64, 0x0
	s_nop 0
	global_load_lds_dwordx4 v76, s[50:51]
	s_add_i32 m0, s64, 0x1000
	s_nop 0
	global_load_lds_dwordx4 v77, s[50:51]
	s_add_i32 m0, s64, 0x2000
	s_nop 0
	global_load_lds_dwordx4 v78, s[50:51]
	s_add_i32 m0, s64, 0x3000
	s_nop 0
	global_load_lds_dwordx4 v79, s[50:51]
	s_add_i32 m0, s64, 0x4000
	s_nop 0
	global_load_lds_dwordx4 v76, s[52:53]
	s_add_i32 m0, s64, 0x5000
	s_nop 0
	global_load_lds_dwordx4 v77, s[52:53]
	s_add_i32 m0, s64, 0x6000
	s_nop 0
	global_load_lds_dwordx4 v78, s[52:53]
	s_add_i32 m0, s64, 0x7000
	s_nop 0
	global_load_lds_dwordx4 v79, s[52:53]
	s_add_u32 s50, s50, 0x80
	s_addc_u32 s51, s51, 0
	s_add_u32 s52, s52, 0x80
	s_addc_u32 s53, s53, 0
	s_setprio 3
	v_mfma_f32_16x16x32_bf16 v[62:65], v[188:191], v[148:151], v[62:65]
	v_mfma_f32_16x16x32_bf16 v[54:57], v[192:195], v[148:151], v[54:57]
	v_mfma_f32_16x16x32_bf16 v[58:61], v[208:211], v[148:151], v[58:61]
	v_mfma_f32_16x16x32_bf16 v[50:53], v[212:215], v[148:151], v[50:53]
	v_mfma_f32_16x16x32_bf16 v[46:49], v[188:191], v[152:155], v[46:49]
	v_mfma_f32_16x16x32_bf16 v[38:41], v[192:195], v[152:155], v[38:41]
	v_mfma_f32_16x16x32_bf16 v[42:45], v[208:211], v[152:155], v[42:45]
	v_mfma_f32_16x16x32_bf16 v[34:37], v[212:215], v[152:155], v[34:37]
	v_mfma_f32_16x16x32_bf16 v[30:33], v[188:191], v[156:159], v[30:33]
	v_mfma_f32_16x16x32_bf16 v[22:25], v[192:195], v[156:159], v[22:25]
	v_mfma_f32_16x16x32_bf16 v[26:29], v[208:211], v[156:159], v[26:29]
	v_mfma_f32_16x16x32_bf16 v[18:21], v[212:215], v[156:159], v[18:21]
	v_mfma_f32_16x16x32_bf16 v[14:17], v[188:191], v[160:163], v[14:17]
	v_mfma_f32_16x16x32_bf16 v[6:9], v[192:195], v[160:163], v[6:9]
	v_mfma_f32_16x16x32_bf16 v[10:13], v[208:211], v[160:163], v[10:13]
	v_mfma_f32_16x16x32_bf16 v[2:5], v[212:215], v[160:163], v[2:5]
	v_mfma_f32_16x16x32_bf16 v[66:69], v[188:191], v[164:167], v[66:69]
	v_mfma_f32_16x16x32_bf16 v[70:73], v[192:195], v[164:167], v[70:73]
	v_mfma_f32_16x16x32_bf16 v[82:85], v[208:211], v[164:167], v[82:85]
	v_mfma_f32_16x16x32_bf16 v[86:89], v[212:215], v[164:167], v[86:89]
	v_mfma_f32_16x16x32_bf16 v[90:93], v[188:191], v[168:171], v[90:93]
	v_mfma_f32_16x16x32_bf16 v[94:97], v[192:195], v[168:171], v[94:97]
	v_mfma_f32_16x16x32_bf16 v[98:101], v[208:211], v[168:171], v[98:101]
	v_mfma_f32_16x16x32_bf16 v[102:105], v[212:215], v[168:171], v[102:105]
	v_mfma_f32_16x16x32_bf16 v[106:109], v[188:191], v[174:177], v[106:109]
	v_mfma_f32_16x16x32_bf16 v[110:113], v[192:195], v[174:177], v[110:113]
	v_mfma_f32_16x16x32_bf16 v[114:117], v[208:211], v[174:177], v[114:117]
	v_mfma_f32_16x16x32_bf16 v[118:121], v[212:215], v[174:177], v[118:121]
	v_mfma_f32_16x16x32_bf16 v[122:125], v[188:191], v[182:185], v[122:125]
	v_mfma_f32_16x16x32_bf16 v[126:129], v[192:195], v[182:185], v[126:129]
	v_mfma_f32_16x16x32_bf16 v[136:139], v[208:211], v[182:185], v[136:139]
	v_mfma_f32_16x16x32_bf16 v[140:143], v[212:215], v[182:185], v[140:143]
	s_setprio 0
	s_waitcnt vmcnt(0)
	s_barrier
	s_add_i32 m0, s64, 0x8000
	s_nop 0
	global_load_lds_dwordx4 v76, s[58:59]
	s_add_i32 m0, s64, 0x9000
	s_nop 0
	global_load_lds_dwordx4 v77, s[58:59]
	s_add_i32 m0, s64, 0xa000
	s_nop 0
	global_load_lds_dwordx4 v78, s[58:59]
	s_add_i32 m0, s64, 0xb000
	s_nop 0
	global_load_lds_dwordx4 v79, s[58:59]
	s_add_u32 s58, s58, 0x80
	s_addc_u32 s59, s59, 0
	ds_read_b128 v[148:151], v80 offset:0
	ds_read_b128 v[152:155], v80 offset:2048
	ds_read_b128 v[156:159], v80 offset:4096
	ds_read_b128 v[160:163], v80 offset:6144
	ds_read_b128 v[188:191], v144 offset:49152
	ds_read_b128 v[192:195], v144 offset:51200
	ds_read_b128 v[208:211], v144 offset:53248
	ds_read_b128 v[212:215], v144 offset:55296
	ds_read_b128 v[164:167], v80 offset:16384
	ds_read_b128 v[168:171], v80 offset:18432
	ds_read_b128 v[174:177], v80 offset:20480
	ds_read_b128 v[182:185], v80 offset:22528
	s_setprio 3
	s_waitcnt lgkmcnt(4)
	v_mfma_f32_16x16x32_bf16 v[62:65], v[188:191], v[148:151], v[62:65]
	v_mfma_f32_16x16x32_bf16 v[54:57], v[192:195], v[148:151], v[54:57]
	v_mfma_f32_16x16x32_bf16 v[58:61], v[208:211], v[148:151], v[58:61]
	v_mfma_f32_16x16x32_bf16 v[50:53], v[212:215], v[148:151], v[50:53]
	v_mfma_f32_16x16x32_bf16 v[46:49], v[188:191], v[152:155], v[46:49]
	v_mfma_f32_16x16x32_bf16 v[38:41], v[192:195], v[152:155], v[38:41]
	v_mfma_f32_16x16x32_bf16 v[42:45], v[208:211], v[152:155], v[42:45]
	v_mfma_f32_16x16x32_bf16 v[34:37], v[212:215], v[152:155], v[34:37]
	v_mfma_f32_16x16x32_bf16 v[30:33], v[188:191], v[156:159], v[30:33]
	v_mfma_f32_16x16x32_bf16 v[22:25], v[192:195], v[156:159], v[22:25]
	v_mfma_f32_16x16x32_bf16 v[26:29], v[208:211], v[156:159], v[26:29]
	v_mfma_f32_16x16x32_bf16 v[18:21], v[212:215], v[156:159], v[18:21]
	v_mfma_f32_16x16x32_bf16 v[14:17], v[188:191], v[160:163], v[14:17]
	v_mfma_f32_16x16x32_bf16 v[6:9], v[192:195], v[160:163], v[6:9]
	v_mfma_f32_16x16x32_bf16 v[10:13], v[208:211], v[160:163], v[10:13]
	v_mfma_f32_16x16x32_bf16 v[2:5], v[212:215], v[160:163], v[2:5]
	s_waitcnt lgkmcnt(0)
	v_mfma_f32_16x16x32_bf16 v[66:69], v[188:191], v[164:167], v[66:69]
	v_mfma_f32_16x16x32_bf16 v[70:73], v[192:195], v[164:167], v[70:73]
	v_mfma_f32_16x16x32_bf16 v[82:85], v[208:211], v[164:167], v[82:85]
	v_mfma_f32_16x16x32_bf16 v[86:89], v[212:215], v[164:167], v[86:89]
	v_mfma_f32_16x16x32_bf16 v[90:93], v[188:191], v[168:171], v[90:93]
	v_mfma_f32_16x16x32_bf16 v[94:97], v[192:195], v[168:171], v[94:97]
	v_mfma_f32_16x16x32_bf16 v[98:101], v[208:211], v[168:171], v[98:101]
	v_mfma_f32_16x16x32_bf16 v[102:105], v[212:215], v[168:171], v[102:105]
	v_mfma_f32_16x16x32_bf16 v[106:109], v[188:191], v[174:177], v[106:109]
	v_mfma_f32_16x16x32_bf16 v[110:113], v[192:195], v[174:177], v[110:113]
	v_mfma_f32_16x16x32_bf16 v[114:117], v[208:211], v[174:177], v[114:117]
	v_mfma_f32_16x16x32_bf16 v[118:121], v[212:215], v[174:177], v[118:121]
	v_mfma_f32_16x16x32_bf16 v[122:125], v[188:191], v[182:185], v[122:125]
	v_mfma_f32_16x16x32_bf16 v[126:129], v[192:195], v[182:185], v[126:129]
	v_mfma_f32_16x16x32_bf16 v[136:139], v[208:211], v[182:185], v[136:139]
	v_mfma_f32_16x16x32_bf16 v[140:143], v[212:215], v[182:185], v[140:143]
	s_setprio 0
	ds_read_b128 v[148:151], v81 offset:0
	ds_read_b128 v[152:155], v81 offset:2048
	ds_read_b128 v[156:159], v81 offset:4096
	ds_read_b128 v[160:163], v81 offset:6144
	ds_read_b128 v[188:191], v145 offset:49152
	ds_read_b128 v[192:195], v145 offset:51200
	ds_read_b128 v[208:211], v145 offset:53248
	ds_read_b128 v[212:215], v145 offset:55296
	ds_read_b128 v[164:167], v81 offset:16384
	ds_read_b128 v[168:171], v81 offset:18432
	ds_read_b128 v[174:177], v81 offset:20480
	ds_read_b128 v[182:185], v81 offset:22528
	s_waitcnt lgkmcnt(0)
	s_barrier
	s_add_i32 m0, s64, 0x0
	s_nop 0
	global_load_lds_dwordx4 v76, s[50:51]
	s_add_i32 m0, s64, 0x1000
	s_nop 0
	global_load_lds_dwordx4 v77, s[50:51]
	s_add_i32 m0, s64, 0x2000
	s_nop 0
	global_load_lds_dwordx4 v78, s[50:51]
	s_add_i32 m0, s64, 0x3000
	s_nop 0
	global_load_lds_dwordx4 v79, s[50:51]
	s_add_i32 m0, s64, 0x4000
	s_nop 0
	global_load_lds_dwordx4 v76, s[52:53]
	s_add_i32 m0, s64, 0x5000
	s_nop 0
	global_load_lds_dwordx4 v77, s[52:53]
	s_add_i32 m0, s64, 0x6000
	s_nop 0
	global_load_lds_dwordx4 v78, s[52:53]
	s_add_i32 m0, s64, 0x7000
	s_nop 0
	global_load_lds_dwordx4 v79, s[52:53]
	s_add_u32 s50, s50, 0x80
	s_addc_u32 s51, s51, 0
	s_add_u32 s52, s52, 0x80
	s_addc_u32 s53, s53, 0
	s_setprio 3
	v_mfma_f32_16x16x32_bf16 v[62:65], v[188:191], v[148:151], v[62:65]
	v_mfma_f32_16x16x32_bf16 v[54:57], v[192:195], v[148:151], v[54:57]
	v_mfma_f32_16x16x32_bf16 v[58:61], v[208:211], v[148:151], v[58:61]
	v_mfma_f32_16x16x32_bf16 v[50:53], v[212:215], v[148:151], v[50:53]
	v_mfma_f32_16x16x32_bf16 v[46:49], v[188:191], v[152:155], v[46:49]
	v_mfma_f32_16x16x32_bf16 v[38:41], v[192:195], v[152:155], v[38:41]
	v_mfma_f32_16x16x32_bf16 v[42:45], v[208:211], v[152:155], v[42:45]
	v_mfma_f32_16x16x32_bf16 v[34:37], v[212:215], v[152:155], v[34:37]
	v_mfma_f32_16x16x32_bf16 v[30:33], v[188:191], v[156:159], v[30:33]
	v_mfma_f32_16x16x32_bf16 v[22:25], v[192:195], v[156:159], v[22:25]
	v_mfma_f32_16x16x32_bf16 v[26:29], v[208:211], v[156:159], v[26:29]
	v_mfma_f32_16x16x32_bf16 v[18:21], v[212:215], v[156:159], v[18:21]
	v_mfma_f32_16x16x32_bf16 v[14:17], v[188:191], v[160:163], v[14:17]
	v_mfma_f32_16x16x32_bf16 v[6:9], v[192:195], v[160:163], v[6:9]
	v_mfma_f32_16x16x32_bf16 v[10:13], v[208:211], v[160:163], v[10:13]
	v_mfma_f32_16x16x32_bf16 v[2:5], v[212:215], v[160:163], v[2:5]
	v_mfma_f32_16x16x32_bf16 v[66:69], v[188:191], v[164:167], v[66:69]
	v_mfma_f32_16x16x32_bf16 v[70:73], v[192:195], v[164:167], v[70:73]
	v_mfma_f32_16x16x32_bf16 v[82:85], v[208:211], v[164:167], v[82:85]
	v_mfma_f32_16x16x32_bf16 v[86:89], v[212:215], v[164:167], v[86:89]
	v_mfma_f32_16x16x32_bf16 v[90:93], v[188:191], v[168:171], v[90:93]
	v_mfma_f32_16x16x32_bf16 v[94:97], v[192:195], v[168:171], v[94:97]
	v_mfma_f32_16x16x32_bf16 v[98:101], v[208:211], v[168:171], v[98:101]
	v_mfma_f32_16x16x32_bf16 v[102:105], v[212:215], v[168:171], v[102:105]
	v_mfma_f32_16x16x32_bf16 v[106:109], v[188:191], v[174:177], v[106:109]
	v_mfma_f32_16x16x32_bf16 v[110:113], v[192:195], v[174:177], v[110:113]
	v_mfma_f32_16x16x32_bf16 v[114:117], v[208:211], v[174:177], v[114:117]
	v_mfma_f32_16x16x32_bf16 v[118:121], v[212:215], v[174:177], v[118:121]
	v_mfma_f32_16x16x32_bf16 v[122:125], v[188:191], v[182:185], v[122:125]
	v_mfma_f32_16x16x32_bf16 v[126:129], v[192:195], v[182:185], v[126:129]
	v_mfma_f32_16x16x32_bf16 v[136:139], v[208:211], v[182:185], v[136:139]
	v_mfma_f32_16x16x32_bf16 v[140:143], v[212:215], v[182:185], v[140:143]
	s_setprio 0
	s_add_i32 s65, s65, -1
	s_cmp_lg_u32 s65, 0
	s_cbranch_scc1 .Lf2_k
	s_waitcnt vmcnt(0)
	s_barrier
	s_add_i32 m0, s64, 0xc000
	s_nop 0
	global_load_lds_dwordx4 v76, s[58:59]
	s_add_i32 m0, s64, 0xd000
	s_nop 0
	global_load_lds_dwordx4 v77, s[58:59]
	s_add_i32 m0, s64, 0xe000
	s_nop 0
	global_load_lds_dwordx4 v78, s[58:59]
	s_add_i32 m0, s64, 0xf000
	s_nop 0
	global_load_lds_dwordx4 v79, s[58:59]
	s_add_u32 s58, s58, 0x80
	s_addc_u32 s59, s59, 0
	ds_read_b128 v[148:151], v80 offset:0
	ds_read_b128 v[152:155], v80 offset:2048
	ds_read_b128 v[156:159], v80 offset:4096
	ds_read_b128 v[160:163], v80 offset:6144
	ds_read_b128 v[188:191], v144 offset:32768
	ds_read_b128 v[192:195], v144 offset:34816
	ds_read_b128 v[208:211], v144 offset:36864
	ds_read_b128 v[212:215], v144 offset:38912
	ds_read_b128 v[164:167], v80 offset:16384
	ds_read_b128 v[168:171], v80 offset:18432
	ds_read_b128 v[174:177], v80 offset:20480
	ds_read_b128 v[182:185], v80 offset:22528
	s_setprio 3
	s_waitcnt lgkmcnt(4)
	v_mfma_f32_16x16x32_bf16 v[62:65], v[188:191], v[148:151], v[62:65]
	v_mfma_f32_16x16x32_bf16 v[54:57], v[192:195], v[148:151], v[54:57]
	v_mfma_f32_16x16x32_bf16 v[58:61], v[208:211], v[148:151], v[58:61]
	v_mfma_f32_16x16x32_bf16 v[50:53], v[212:215], v[148:151], v[50:53]
	v_mfma_f32_16x16x32_bf16 v[46:49], v[188:191], v[152:155], v[46:49]
	v_mfma_f32_16x16x32_bf16 v[38:41], v[192:195], v[152:155], v[38:41]
	v_mfma_f32_16x16x32_bf16 v[42:45], v[208:211], v[152:155], v[42:45]
	v_mfma_f32_16x16x32_bf16 v[34:37], v[212:215], v[152:155], v[34:37]
	v_mfma_f32_16x16x32_bf16 v[30:33], v[188:191], v[156:159], v[30:33]
	v_mfma_f32_16x16x32_bf16 v[22:25], v[192:195], v[156:159], v[22:25]
	v_mfma_f32_16x16x32_bf16 v[26:29], v[208:211], v[156:159], v[26:29]
	v_mfma_f32_16x16x32_bf16 v[18:21], v[212:215], v[156:159], v[18:21]
	v_mfma_f32_16x16x32_bf16 v[14:17], v[188:191], v[160:163], v[14:17]
	v_mfma_f32_16x16x32_bf16 v[6:9], v[192:195], v[160:163], v[6:9]
	v_mfma_f32_16x16x32_bf16 v[10:13], v[208:211], v[160:163], v[10:13]
	v_mfma_f32_16x16x32_bf16 v[2:5], v[212:215], v[160:163], v[2:5]
	s_waitcnt lgkmcnt(0)
	v_mfma_f32_16x16x32_bf16 v[66:69], v[188:191], v[164:167], v[66:69]
	v_mfma_f32_16x16x32_bf16 v[70:73], v[192:195], v[164:167], v[70:73]
	v_mfma_f32_16x16x32_bf16 v[82:85], v[208:211], v[164:167], v[82:85]
	v_mfma_f32_16x16x32_bf16 v[86:89], v[212:215], v[164:167], v[86:89]
	v_mfma_f32_16x16x32_bf16 v[90:93], v[188:191], v[168:171], v[90:93]
	v_mfma_f32_16x16x32_bf16 v[94:97], v[192:195], v[168:171], v[94:97]
	v_mfma_f32_16x16x32_bf16 v[98:101], v[208:211], v[168:171], v[98:101]
	v_mfma_f32_16x16x32_bf16 v[102:105], v[212:215], v[168:171], v[102:105]
	v_mfma_f32_16x16x32_bf16 v[106:109], v[188:191], v[174:177], v[106:109]
	v_mfma_f32_16x16x32_bf16 v[110:113], v[192:195], v[174:177], v[110:113]
	v_mfma_f32_16x16x32_bf16 v[114:117], v[208:211], v[174:177], v[114:117]
	v_mfma_f32_16x16x32_bf16 v[118:121], v[212:215], v[174:177], v[118:121]
	v_mfma_f32_16x16x32_bf16 v[122:125], v[188:191], v[182:185], v[122:125]
	v_mfma_f32_16x16x32_bf16 v[126:129], v[192:195], v[182:185], v[126:129]
	v_mfma_f32_16x16x32_bf16 v[136:139], v[208:211], v[182:185], v[136:139]
	v_mfma_f32_16x16x32_bf16 v[140:143], v[212:215], v[182:185], v[140:143]
	s_setprio 0
	ds_read_b128 v[148:151], v81 offset:0
	ds_read_b128 v[152:155], v81 offset:2048
	ds_read_b128 v[156:159], v81 offset:4096
	ds_read_b128 v[160:163], v81 offset:6144
	ds_read_b128 v[188:191], v145 offset:32768
	ds_read_b128 v[192:195], v145 offset:34816
	ds_read_b128 v[208:211], v145 offset:36864
	ds_read_b128 v[212:215], v145 offset:38912
	ds_read_b128 v[164:167], v81 offset:16384
	ds_read_b128 v[168:171], v81 offset:18432
	ds_read_b128 v[174:177], v81 offset:20480
	ds_read_b128 v[182:185], v81 offset:22528
	s_waitcnt lgkmcnt(0)
	s_barrier
	s_add_i32 m0, s64, 0x0
	s_nop 0
	global_load_lds_dwordx4 v76, s[50:51]
	s_add_i32 m0, s64, 0x1000
	s_nop 0
	global_load_lds_dwordx4 v77, s[50:51]
	s_add_i32 m0, s64, 0x2000
	s_nop 0
	global_load_lds_dwordx4 v78, s[50:51]
	s_add_i32 m0, s64, 0x3000
	s_nop 0
	global_load_lds_dwordx4 v79, s[50:51]
	s_add_i32 m0, s64, 0x4000
	s_nop 0
	global_load_lds_dwordx4 v76, s[52:53]
	s_add_i32 m0, s64, 0x5000
	s_nop 0
	global_load_lds_dwordx4 v77, s[52:53]
	s_add_i32 m0, s64, 0x6000
	s_nop 0
	global_load_lds_dwordx4 v78, s[52:53]
	s_add_i32 m0, s64, 0x7000
	s_nop 0
	global_load_lds_dwordx4 v79, s[52:53]
	s_add_u32 s50, s50, 0x80
	s_addc_u32 s51, s51, 0
	s_add_u32 s52, s52, 0x80
	s_addc_u32 s53, s53, 0
	s_setprio 3
	v_mfma_f32_16x16x32_bf16 v[62:65], v[188:191], v[148:151], v[62:65]
	v_mfma_f32_16x16x32_bf16 v[54:57], v[192:195], v[148:151], v[54:57]
	v_mfma_f32_16x16x32_bf16 v[58:61], v[208:211], v[148:151], v[58:61]
	v_mfma_f32_16x16x32_bf16 v[50:53], v[212:215], v[148:151], v[50:53]
	v_mfma_f32_16x16x32_bf16 v[46:49], v[188:191], v[152:155], v[46:49]
	v_mfma_f32_16x16x32_bf16 v[38:41], v[192:195], v[152:155], v[38:41]
	v_mfma_f32_16x16x32_bf16 v[42:45], v[208:211], v[152:155], v[42:45]
	v_mfma_f32_16x16x32_bf16 v[34:37], v[212:215], v[152:155], v[34:37]
	v_mfma_f32_16x16x32_bf16 v[30:33], v[188:191], v[156:159], v[30:33]
	v_mfma_f32_16x16x32_bf16 v[22:25], v[192:195], v[156:159], v[22:25]
	v_mfma_f32_16x16x32_bf16 v[26:29], v[208:211], v[156:159], v[26:29]
	v_mfma_f32_16x16x32_bf16 v[18:21], v[212:215], v[156:159], v[18:21]
	v_mfma_f32_16x16x32_bf16 v[14:17], v[188:191], v[160:163], v[14:17]
	v_mfma_f32_16x16x32_bf16 v[6:9], v[192:195], v[160:163], v[6:9]
	v_mfma_f32_16x16x32_bf16 v[10:13], v[208:211], v[160:163], v[10:13]
	v_mfma_f32_16x16x32_bf16 v[2:5], v[212:215], v[160:163], v[2:5]
	v_mfma_f32_16x16x32_bf16 v[66:69], v[188:191], v[164:167], v[66:69]
	v_mfma_f32_16x16x32_bf16 v[70:73], v[192:195], v[164:167], v[70:73]
	v_mfma_f32_16x16x32_bf16 v[82:85], v[208:211], v[164:167], v[82:85]
	v_mfma_f32_16x16x32_bf16 v[86:89], v[212:215], v[164:167], v[86:89]
	v_mfma_f32_16x16x32_bf16 v[90:93], v[188:191], v[168:171], v[90:93]
	v_mfma_f32_16x16x32_bf16 v[94:97], v[192:195], v[168:171], v[94:97]
	v_mfma_f32_16x16x32_bf16 v[98:101], v[208:211], v[168:171], v[98:101]
	v_mfma_f32_16x16x32_bf16 v[102:105], v[212:215], v[168:171], v[102:105]
	v_mfma_f32_16x16x32_bf16 v[106:109], v[188:191], v[174:177], v[106:109]
	v_mfma_f32_16x16x32_bf16 v[110:113], v[192:195], v[174:177], v[110:113]
	v_mfma_f32_16x16x32_bf16 v[114:117], v[208:211], v[174:177], v[114:117]
	v_mfma_f32_16x16x32_bf16 v[118:121], v[212:215], v[174:177], v[118:121]
	v_mfma_f32_16x16x32_bf16 v[122:125], v[188:191], v[182:185], v[122:125]
	v_mfma_f32_16x16x32_bf16 v[126:129], v[192:195], v[182:185], v[126:129]
	v_mfma_f32_16x16x32_bf16 v[136:139], v[208:211], v[182:185], v[136:139]
	v_mfma_f32_16x16x32_bf16 v[140:143], v[212:215], v[182:185], v[140:143]
	s_setprio 0
	s_waitcnt vmcnt(0)
	s_barrier
	ds_read_b128 v[148:151], v80 offset:0
	ds_read_b128 v[152:155], v80 offset:2048
	ds_read_b128 v[156:159], v80 offset:4096
	ds_read_b128 v[160:163], v80 offset:6144
	ds_read_b128 v[188:191], v144 offset:49152
	ds_read_b128 v[192:195], v144 offset:51200
	ds_read_b128 v[208:211], v144 offset:53248
	ds_read_b128 v[212:215], v144 offset:55296
	ds_read_b128 v[164:167], v80 offset:16384
	ds_read_b128 v[168:171], v80 offset:18432
	ds_read_b128 v[174:177], v80 offset:20480
	ds_read_b128 v[182:185], v80 offset:22528
	s_setprio 3
	s_waitcnt lgkmcnt(4)
	v_mfma_f32_16x16x32_bf16 v[62:65], v[188:191], v[148:151], v[62:65]
	v_mfma_f32_16x16x32_bf16 v[54:57], v[192:195], v[148:151], v[54:57]
	v_mfma_f32_16x16x32_bf16 v[58:61], v[208:211], v[148:151], v[58:61]
	v_mfma_f32_16x16x32_bf16 v[50:53], v[212:215], v[148:151], v[50:53]
	v_mfma_f32_16x16x32_bf16 v[46:49], v[188:191], v[152:155], v[46:49]
	v_mfma_f32_16x16x32_bf16 v[38:41], v[192:195], v[152:155], v[38:41]
	v_mfma_f32_16x16x32_bf16 v[42:45], v[208:211], v[152:155], v[42:45]
	v_mfma_f32_16x16x32_bf16 v[34:37], v[212:215], v[152:155], v[34:37]
	v_mfma_f32_16x16x32_bf16 v[30:33], v[188:191], v[156:159], v[30:33]
	v_mfma_f32_16x16x32_bf16 v[22:25], v[192:195], v[156:159], v[22:25]
	v_mfma_f32_16x16x32_bf16 v[26:29], v[208:211], v[156:159], v[26:29]
	v_mfma_f32_16x16x32_bf16 v[18:21], v[212:215], v[156:159], v[18:21]
	v_mfma_f32_16x16x32_bf16 v[14:17], v[188:191], v[160:163], v[14:17]
	v_mfma_f32_16x16x32_bf16 v[6:9], v[192:195], v[160:163], v[6:9]
	v_mfma_f32_16x16x32_bf16 v[10:13], v[208:211], v[160:163], v[10:13]
	v_mfma_f32_16x16x32_bf16 v[2:5], v[212:215], v[160:163], v[2:5]
	s_waitcnt lgkmcnt(0)
	v_mfma_f32_16x16x32_bf16 v[66:69], v[188:191], v[164:167], v[66:69]
	v_mfma_f32_16x16x32_bf16 v[70:73], v[192:195], v[164:167], v[70:73]
	v_mfma_f32_16x16x32_bf16 v[82:85], v[208:211], v[164:167], v[82:85]
	v_mfma_f32_16x16x32_bf16 v[86:89], v[212:215], v[164:167], v[86:89]
	v_mfma_f32_16x16x32_bf16 v[90:93], v[188:191], v[168:171], v[90:93]
	v_mfma_f32_16x16x32_bf16 v[94:97], v[192:195], v[168:171], v[94:97]
	v_mfma_f32_16x16x32_bf16 v[98:101], v[208:211], v[168:171], v[98:101]
	v_mfma_f32_16x16x32_bf16 v[102:105], v[212:215], v[168:171], v[102:105]
	v_mfma_f32_16x16x32_bf16 v[106:109], v[188:191], v[174:177], v[106:109]
	v_mfma_f32_16x16x32_bf16 v[110:113], v[192:195], v[174:177], v[110:113]
	v_mfma_f32_16x16x32_bf16 v[114:117], v[208:211], v[174:177], v[114:117]
	v_mfma_f32_16x16x32_bf16 v[118:121], v[212:215], v[174:177], v[118:121]
	v_mfma_f32_16x16x32_bf16 v[122:125], v[188:191], v[182:185], v[122:125]
	v_mfma_f32_16x16x32_bf16 v[126:129], v[192:195], v[182:185], v[126:129]
	v_mfma_f32_16x16x32_bf16 v[136:139], v[208:211], v[182:185], v[136:139]
	v_mfma_f32_16x16x32_bf16 v[140:143], v[212:215], v[182:185], v[140:143]
	s_setprio 0
	ds_read_b128 v[148:151], v81 offset:0
	ds_read_b128 v[152:155], v81 offset:2048
	ds_read_b128 v[156:159], v81 offset:4096
	ds_read_b128 v[160:163], v81 offset:6144
	ds_read_b128 v[188:191], v145 offset:49152
	ds_read_b128 v[192:195], v145 offset:51200
	ds_read_b128 v[208:211], v145 offset:53248
	ds_read_b128 v[212:215], v145 offset:55296
	ds_read_b128 v[164:167], v81 offset:16384
	ds_read_b128 v[168:171], v81 offset:18432
	ds_read_b128 v[174:177], v81 offset:20480
	ds_read_b128 v[182:185], v81 offset:22528
	s_setprio 3
	s_waitcnt lgkmcnt(4)
	v_mfma_f32_16x16x32_bf16 v[62:65], v[188:191], v[148:151], v[62:65]
	v_mfma_f32_16x16x32_bf16 v[54:57], v[192:195], v[148:151], v[54:57]
	v_mfma_f32_16x16x32_bf16 v[58:61], v[208:211], v[148:151], v[58:61]
	v_mfma_f32_16x16x32_bf16 v[50:53], v[212:215], v[148:151], v[50:53]
	v_mfma_f32_16x16x32_bf16 v[46:49], v[188:191], v[152:155], v[46:49]
	v_mfma_f32_16x16x32_bf16 v[38:41], v[192:195], v[152:155], v[38:41]
	v_mfma_f32_16x16x32_bf16 v[42:45], v[208:211], v[152:155], v[42:45]
	v_mfma_f32_16x16x32_bf16 v[34:37], v[212:215], v[152:155], v[34:37]
	v_mfma_f32_16x16x32_bf16 v[30:33], v[188:191], v[156:159], v[30:33]
	v_mfma_f32_16x16x32_bf16 v[22:25], v[192:195], v[156:159], v[22:25]
	v_mfma_f32_16x16x32_bf16 v[26:29], v[208:211], v[156:159], v[26:29]
	v_mfma_f32_16x16x32_bf16 v[18:21], v[212:215], v[156:159], v[18:21]
	v_mfma_f32_16x16x32_bf16 v[14:17], v[188:191], v[160:163], v[14:17]
	v_mfma_f32_16x16x32_bf16 v[6:9], v[192:195], v[160:163], v[6:9]
	v_mfma_f32_16x16x32_bf16 v[10:13], v[208:211], v[160:163], v[10:13]
	v_mfma_f32_16x16x32_bf16 v[2:5], v[212:215], v[160:163], v[2:5]
	s_waitcnt lgkmcnt(0)
	v_mfma_f32_16x16x32_bf16 v[66:69], v[188:191], v[164:167], v[66:69]
	v_mfma_f32_16x16x32_bf16 v[70:73], v[192:195], v[164:167], v[70:73]
	v_mfma_f32_16x16x32_bf16 v[82:85], v[208:211], v[164:167], v[82:85]
	v_mfma_f32_16x16x32_bf16 v[86:89], v[212:215], v[164:167], v[86:89]
	v_mfma_f32_16x16x32_bf16 v[90:93], v[188:191], v[168:171], v[90:93]
	v_mfma_f32_16x16x32_bf16 v[94:97], v[192:195], v[168:171], v[94:97]
	v_mfma_f32_16x16x32_bf16 v[98:101], v[208:211], v[168:171], v[98:101]
	v_mfma_f32_16x16x32_bf16 v[102:105], v[212:215], v[168:171], v[102:105]
	v_mfma_f32_16x16x32_bf16 v[106:109], v[188:191], v[174:177], v[106:109]
	v_mfma_f32_16x16x32_bf16 v[110:113], v[192:195], v[174:177], v[110:113]
	v_mfma_f32_16x16x32_bf16 v[114:117], v[208:211], v[174:177], v[114:117]
	v_mfma_f32_16x16x32_bf16 v[118:121], v[212:215], v[174:177], v[118:121]
	v_mfma_f32_16x16x32_bf16 v[122:125], v[188:191], v[182:185], v[122:125]
	v_mfma_f32_16x16x32_bf16 v[126:129], v[192:195], v[182:185], v[126:129]
	v_mfma_f32_16x16x32_bf16 v[136:139], v[208:211], v[182:185], v[136:139]
	v_mfma_f32_16x16x32_bf16 v[140:143], v[212:215], v[182:185], v[140:143]
	s_setprio 0
	s_nop 7
	s_nop 7
	s_nop 7
	s_add_i32 s48, s48, 1
	s_mov_b32 s39, 0
	v_readlane_b32 s30, v249, 0
	s_nop 0
	s_and_b32 s31, s30, 7
	s_lshr_b32 s30, s30, 3
	s_cmp_lt_u32 s30, 32
	s_cselect_b32 s35, 6, 5
	s_cmp_lt_u32 s48, s35
	s_cbranch_scc0 .Lf2_c1_extra
	s_lshl_b32 s33, s48, 6
	s_add_i32 s33, s33, s30
	s_cmp_ge_u32 s33, 0xb0
	s_cselect_b32 s34, 1, 0
	s_mul_i32 s36, s34, 0xb0
	s_sub_i32 s33, s33, s36
	s_lshr_b32 s37, s33, 2
	s_and_b32 s33, s33, 3
	s_lshl_b32 s34, s34, 3
	s_add_i32 s33, s33, s34
	s_lshl_b32 s33, s33, 3
	s_add_i32 s36, s33, s31
	s_add_i32 s38, s36, 32
	s_branch .Lf2_c1_have

.Lr2o_k:
	s_waitcnt vmcnt(0)
	s_barrier
	s_add_i32 m0, s36, 0xc000
	s_nop 0
	global_load_lds_dwordx4 v136, s[34:35]
	s_add_i32 m0, s36, 0xd000
	s_nop 0
	global_load_lds_dwordx4 v137, s[34:35]
	s_add_i32 m0, s36, 0xe000
	s_nop 0
	global_load_lds_dwordx4 v138, s[34:35]
	s_add_i32 m0, s36, 0xf000
	s_nop 0
	global_load_lds_dwordx4 v139, s[34:35]
	s_add_u32 s34, s34, 0x80
	s_addc_u32 s35, s35, 0
	ds_read_b128 v[148:151], v140 offset:0
	ds_read_b128 v[152:155], v140 offset:2048
	ds_read_b128 v[156:159], v140 offset:4096
	ds_read_b128 v[160:163], v140 offset:6144
	ds_read_b128 v[164:167], v140 offset:16384
	ds_read_b128 v[168:171], v140 offset:18432
	ds_read_b128 v[174:177], v140 offset:20480
	ds_read_b128 v[182:185], v140 offset:22528
	ds_read_b128 v[188:191], v142 offset:32768
	ds_read_b128 v[192:195], v142 offset:34816
	ds_read_b128 v[208:211], v142 offset:36864
	ds_read_b128 v[212:215], v142 offset:38912
	s_waitcnt lgkmcnt(0)
	s_setprio 3
	v_mfma_f32_16x16x32_bf16 v[62:65], v[188:191], v[148:151], v[62:65]
	v_mfma_f32_16x16x32_bf16 v[58:61], v[192:195], v[148:151], v[58:61]
	v_mfma_f32_16x16x32_bf16 v[54:57], v[208:211], v[148:151], v[54:57]
	v_mfma_f32_16x16x32_bf16 v[50:53], v[212:215], v[148:151], v[50:53]
	v_mfma_f32_16x16x32_bf16 v[46:49], v[188:191], v[152:155], v[46:49]
	v_mfma_f32_16x16x32_bf16 v[42:45], v[192:195], v[152:155], v[42:45]
	v_mfma_f32_16x16x32_bf16 v[38:41], v[208:211], v[152:155], v[38:41]
	v_mfma_f32_16x16x32_bf16 v[34:37], v[212:215], v[152:155], v[34:37]
	v_mfma_f32_16x16x32_bf16 v[30:33], v[188:191], v[156:159], v[30:33]
	v_mfma_f32_16x16x32_bf16 v[26:29], v[192:195], v[156:159], v[26:29]
	v_mfma_f32_16x16x32_bf16 v[22:25], v[208:211], v[156:159], v[22:25]
	v_mfma_f32_16x16x32_bf16 v[18:21], v[212:215], v[156:159], v[18:21]
	v_mfma_f32_16x16x32_bf16 v[14:17], v[188:191], v[160:163], v[14:17]
	v_mfma_f32_16x16x32_bf16 v[10:13], v[192:195], v[160:163], v[10:13]
	v_mfma_f32_16x16x32_bf16 v[6:9], v[208:211], v[160:163], v[6:9]
	v_mfma_f32_16x16x32_bf16 v[2:5], v[212:215], v[160:163], v[2:5]
	v_mfma_f32_16x16x32_bf16 v[66:69], v[188:191], v[164:167], v[66:69]
	v_mfma_f32_16x16x32_bf16 v[70:73], v[192:195], v[164:167], v[70:73]
	v_mfma_f32_16x16x32_bf16 v[74:77], v[208:211], v[164:167], v[74:77]
	v_mfma_f32_16x16x32_bf16 v[78:81], v[212:215], v[164:167], v[78:81]
	v_mfma_f32_16x16x32_bf16 v[82:85], v[188:191], v[168:171], v[82:85]
	v_mfma_f32_16x16x32_bf16 v[86:89], v[192:195], v[168:171], v[86:89]
	v_mfma_f32_16x16x32_bf16 v[90:93], v[208:211], v[168:171], v[90:93]
	v_mfma_f32_16x16x32_bf16 v[94:97], v[212:215], v[168:171], v[94:97]
	v_mfma_f32_16x16x32_bf16 v[98:101], v[188:191], v[174:177], v[98:101]
	v_mfma_f32_16x16x32_bf16 v[102:105], v[192:195], v[174:177], v[102:105]
	v_mfma_f32_16x16x32_bf16 v[106:109], v[208:211], v[174:177], v[106:109]
	v_mfma_f32_16x16x32_bf16 v[110:113], v[212:215], v[174:177], v[110:113]
	v_mfma_f32_16x16x32_bf16 v[114:117], v[188:191], v[182:185], v[114:117]
	v_mfma_f32_16x16x32_bf16 v[118:121], v[192:195], v[182:185], v[118:121]
	v_mfma_f32_16x16x32_bf16 v[122:125], v[208:211], v[182:185], v[122:125]
	v_mfma_f32_16x16x32_bf16 v[126:129], v[212:215], v[182:185], v[126:129]
	s_setprio 0
	ds_read_b128 v[148:151], v141 offset:0
	ds_read_b128 v[152:155], v141 offset:2048
	ds_read_b128 v[156:159], v141 offset:4096
	ds_read_b128 v[160:163], v141 offset:6144
	ds_read_b128 v[164:167], v141 offset:16384
	ds_read_b128 v[168:171], v141 offset:18432
	ds_read_b128 v[174:177], v141 offset:20480
	ds_read_b128 v[182:185], v141 offset:22528
	ds_read_b128 v[188:191], v143 offset:32768
	ds_read_b128 v[192:195], v143 offset:34816
	ds_read_b128 v[208:211], v143 offset:36864
	ds_read_b128 v[212:215], v143 offset:38912
	s_waitcnt lgkmcnt(0)
	s_barrier
	s_add_i32 m0, s36, 0x0
	s_nop 0
	global_load_lds_dwordx4 v136, s[30:31]
	s_add_i32 m0, s36, 0x1000
	s_nop 0
	global_load_lds_dwordx4 v137, s[30:31]
	s_add_i32 m0, s36, 0x2000
	s_nop 0
	global_load_lds_dwordx4 v138, s[30:31]
	s_add_i32 m0, s36, 0x3000
	s_nop 0
	global_load_lds_dwordx4 v139, s[30:31]
	s_add_i32 m0, s36, 0x4000
	s_nop 0
	global_load_lds_dwordx4 v136, s[44:45]
	s_add_i32 m0, s36, 0x5000
	s_nop 0
	global_load_lds_dwordx4 v137, s[44:45]
	s_add_i32 m0, s36, 0x6000
	s_nop 0
	global_load_lds_dwordx4 v138, s[44:45]
	s_add_i32 m0, s36, 0x7000
	s_nop 0
	global_load_lds_dwordx4 v139, s[44:45]
	s_add_u32 s30, s30, 0x80
	s_addc_u32 s31, s31, 0
	s_add_u32 s44, s44, 0x80
	s_addc_u32 s45, s45, 0
	s_setprio 3
	v_mfma_f32_16x16x32_bf16 v[62:65], v[188:191], v[148:151], v[62:65]
	v_mfma_f32_16x16x32_bf16 v[58:61], v[192:195], v[148:151], v[58:61]
	v_mfma_f32_16x16x32_bf16 v[54:57], v[208:211], v[148:151], v[54:57]
	v_mfma_f32_16x16x32_bf16 v[50:53], v[212:215], v[148:151], v[50:53]
	v_mfma_f32_16x16x32_bf16 v[46:49], v[188:191], v[152:155], v[46:49]
	v_mfma_f32_16x16x32_bf16 v[42:45], v[192:195], v[152:155], v[42:45]
	v_mfma_f32_16x16x32_bf16 v[38:41], v[208:211], v[152:155], v[38:41]
	v_mfma_f32_16x16x32_bf16 v[34:37], v[212:215], v[152:155], v[34:37]
	v_mfma_f32_16x16x32_bf16 v[30:33], v[188:191], v[156:159], v[30:33]
	v_mfma_f32_16x16x32_bf16 v[26:29], v[192:195], v[156:159], v[26:29]
	v_mfma_f32_16x16x32_bf16 v[22:25], v[208:211], v[156:159], v[22:25]
	v_mfma_f32_16x16x32_bf16 v[18:21], v[212:215], v[156:159], v[18:21]
	v_mfma_f32_16x16x32_bf16 v[14:17], v[188:191], v[160:163], v[14:17]
	v_mfma_f32_16x16x32_bf16 v[10:13], v[192:195], v[160:163], v[10:13]
	v_mfma_f32_16x16x32_bf16 v[6:9], v[208:211], v[160:163], v[6:9]
	v_mfma_f32_16x16x32_bf16 v[2:5], v[212:215], v[160:163], v[2:5]
	v_mfma_f32_16x16x32_bf16 v[66:69], v[188:191], v[164:167], v[66:69]
	v_mfma_f32_16x16x32_bf16 v[70:73], v[192:195], v[164:167], v[70:73]
	v_mfma_f32_16x16x32_bf16 v[74:77], v[208:211], v[164:167], v[74:77]
	v_mfma_f32_16x16x32_bf16 v[78:81], v[212:215], v[164:167], v[78:81]
	v_mfma_f32_16x16x32_bf16 v[82:85], v[188:191], v[168:171], v[82:85]
	v_mfma_f32_16x16x32_bf16 v[86:89], v[192:195], v[168:171], v[86:89]
	v_mfma_f32_16x16x32_bf16 v[90:93], v[208:211], v[168:171], v[90:93]
	v_mfma_f32_16x16x32_bf16 v[94:97], v[212:215], v[168:171], v[94:97]
	v_mfma_f32_16x16x32_bf16 v[98:101], v[188:191], v[174:177], v[98:101]
	v_mfma_f32_16x16x32_bf16 v[102:105], v[192:195], v[174:177], v[102:105]
	v_mfma_f32_16x16x32_bf16 v[106:109], v[208:211], v[174:177], v[106:109]
	v_mfma_f32_16x16x32_bf16 v[110:113], v[212:215], v[174:177], v[110:113]
	v_mfma_f32_16x16x32_bf16 v[114:117], v[188:191], v[182:185], v[114:117]
	v_mfma_f32_16x16x32_bf16 v[118:121], v[192:195], v[182:185], v[118:121]
	v_mfma_f32_16x16x32_bf16 v[122:125], v[208:211], v[182:185], v[122:125]
	v_mfma_f32_16x16x32_bf16 v[126:129], v[212:215], v[182:185], v[126:129]
	s_setprio 0
	s_waitcnt vmcnt(0)
	s_barrier
	s_add_i32 m0, s36, 0x8000
	s_nop 0
	global_load_lds_dwordx4 v136, s[34:35]
	s_add_i32 m0, s36, 0x9000
	s_nop 0
	global_load_lds_dwordx4 v137, s[34:35]
	s_add_i32 m0, s36, 0xa000
	s_nop 0
	global_load_lds_dwordx4 v138, s[34:35]
	s_add_i32 m0, s36, 0xb000
	s_nop 0
	global_load_lds_dwordx4 v139, s[34:35]
	s_add_u32 s34, s34, 0x80
	s_addc_u32 s35, s35, 0
	ds_read_b128 v[148:151], v140 offset:0
	ds_read_b128 v[152:155], v140 offset:2048
	ds_read_b128 v[156:159], v140 offset:4096
	ds_read_b128 v[160:163], v140 offset:6144
	ds_read_b128 v[164:167], v140 offset:16384
	ds_read_b128 v[168:171], v140 offset:18432
	ds_read_b128 v[174:177], v140 offset:20480
	ds_read_b128 v[182:185], v140 offset:22528
	ds_read_b128 v[188:191], v142 offset:49152
	ds_read_b128 v[192:195], v142 offset:51200
	ds_read_b128 v[208:211], v142 offset:53248
	ds_read_b128 v[212:215], v142 offset:55296
	s_waitcnt lgkmcnt(0)
	s_setprio 3
	v_mfma_f32_16x16x32_bf16 v[62:65], v[188:191], v[148:151], v[62:65]
	v_mfma_f32_16x16x32_bf16 v[58:61], v[192:195], v[148:151], v[58:61]
	v_mfma_f32_16x16x32_bf16 v[54:57], v[208:211], v[148:151], v[54:57]
	v_mfma_f32_16x16x32_bf16 v[50:53], v[212:215], v[148:151], v[50:53]
	v_mfma_f32_16x16x32_bf16 v[46:49], v[188:191], v[152:155], v[46:49]
	v_mfma_f32_16x16x32_bf16 v[42:45], v[192:195], v[152:155], v[42:45]
	v_mfma_f32_16x16x32_bf16 v[38:41], v[208:211], v[152:155], v[38:41]
	v_mfma_f32_16x16x32_bf16 v[34:37], v[212:215], v[152:155], v[34:37]
	v_mfma_f32_16x16x32_bf16 v[30:33], v[188:191], v[156:159], v[30:33]
	v_mfma_f32_16x16x32_bf16 v[26:29], v[192:195], v[156:159], v[26:29]
	v_mfma_f32_16x16x32_bf16 v[22:25], v[208:211], v[156:159], v[22:25]
	v_mfma_f32_16x16x32_bf16 v[18:21], v[212:215], v[156:159], v[18:21]
	v_mfma_f32_16x16x32_bf16 v[14:17], v[188:191], v[160:163], v[14:17]
	v_mfma_f32_16x16x32_bf16 v[10:13], v[192:195], v[160:163], v[10:13]
	v_mfma_f32_16x16x32_bf16 v[6:9], v[208:211], v[160:163], v[6:9]
	v_mfma_f32_16x16x32_bf16 v[2:5], v[212:215], v[160:163], v[2:5]
	v_mfma_f32_16x16x32_bf16 v[66:69], v[188:191], v[164:167], v[66:69]
	v_mfma_f32_16x16x32_bf16 v[70:73], v[192:195], v[164:167], v[70:73]
	v_mfma_f32_16x16x32_bf16 v[74:77], v[208:211], v[164:167], v[74:77]
	v_mfma_f32_16x16x32_bf16 v[78:81], v[212:215], v[164:167], v[78:81]
	v_mfma_f32_16x16x32_bf16 v[82:85], v[188:191], v[168:171], v[82:85]
	v_mfma_f32_16x16x32_bf16 v[86:89], v[192:195], v[168:171], v[86:89]
	v_mfma_f32_16x16x32_bf16 v[90:93], v[208:211], v[168:171], v[90:93]
	v_mfma_f32_16x16x32_bf16 v[94:97], v[212:215], v[168:171], v[94:97]
	v_mfma_f32_16x16x32_bf16 v[98:101], v[188:191], v[174:177], v[98:101]
	v_mfma_f32_16x16x32_bf16 v[102:105], v[192:195], v[174:177], v[102:105]
	v_mfma_f32_16x16x32_bf16 v[106:109], v[208:211], v[174:177], v[106:109]
	v_mfma_f32_16x16x32_bf16 v[110:113], v[212:215], v[174:177], v[110:113]
	v_mfma_f32_16x16x32_bf16 v[114:117], v[188:191], v[182:185], v[114:117]
	v_mfma_f32_16x16x32_bf16 v[118:121], v[192:195], v[182:185], v[118:121]
	v_mfma_f32_16x16x32_bf16 v[122:125], v[208:211], v[182:185], v[122:125]
	v_mfma_f32_16x16x32_bf16 v[126:129], v[212:215], v[182:185], v[126:129]
	s_setprio 0
	ds_read_b128 v[148:151], v141 offset:0
	ds_read_b128 v[152:155], v141 offset:2048
	ds_read_b128 v[156:159], v141 offset:4096
	ds_read_b128 v[160:163], v141 offset:6144
	ds_read_b128 v[164:167], v141 offset:16384
	ds_read_b128 v[168:171], v141 offset:18432
	ds_read_b128 v[174:177], v141 offset:20480
	ds_read_b128 v[182:185], v141 offset:22528
	ds_read_b128 v[188:191], v143 offset:49152
	ds_read_b128 v[192:195], v143 offset:51200
	ds_read_b128 v[208:211], v143 offset:53248
	ds_read_b128 v[212:215], v143 offset:55296
	s_waitcnt lgkmcnt(0)
	s_barrier
	s_add_i32 m0, s36, 0x0
	s_nop 0
	global_load_lds_dwordx4 v136, s[30:31]
	s_add_i32 m0, s36, 0x1000
	s_nop 0
	global_load_lds_dwordx4 v137, s[30:31]
	s_add_i32 m0, s36, 0x2000
	s_nop 0
	global_load_lds_dwordx4 v138, s[30:31]
	s_add_i32 m0, s36, 0x3000
	s_nop 0
	global_load_lds_dwordx4 v139, s[30:31]
	s_add_i32 m0, s36, 0x4000
	s_nop 0
	global_load_lds_dwordx4 v136, s[44:45]
	s_add_i32 m0, s36, 0x5000
	s_nop 0
	global_load_lds_dwordx4 v137, s[44:45]
	s_add_i32 m0, s36, 0x6000
	s_nop 0
	global_load_lds_dwordx4 v138, s[44:45]
	s_add_i32 m0, s36, 0x7000
	s_nop 0
	global_load_lds_dwordx4 v139, s[44:45]
	s_add_u32 s30, s30, 0x80
	s_addc_u32 s31, s31, 0
	s_add_u32 s44, s44, 0x80
	s_addc_u32 s45, s45, 0
	s_setprio 3
	v_mfma_f32_16x16x32_bf16 v[62:65], v[188:191], v[148:151], v[62:65]
	v_mfma_f32_16x16x32_bf16 v[58:61], v[192:195], v[148:151], v[58:61]
	v_mfma_f32_16x16x32_bf16 v[54:57], v[208:211], v[148:151], v[54:57]
	v_mfma_f32_16x16x32_bf16 v[50:53], v[212:215], v[148:151], v[50:53]
	v_mfma_f32_16x16x32_bf16 v[46:49], v[188:191], v[152:155], v[46:49]
	v_mfma_f32_16x16x32_bf16 v[42:45], v[192:195], v[152:155], v[42:45]
	v_mfma_f32_16x16x32_bf16 v[38:41], v[208:211], v[152:155], v[38:41]
	v_mfma_f32_16x16x32_bf16 v[34:37], v[212:215], v[152:155], v[34:37]
	v_mfma_f32_16x16x32_bf16 v[30:33], v[188:191], v[156:159], v[30:33]
	v_mfma_f32_16x16x32_bf16 v[26:29], v[192:195], v[156:159], v[26:29]
	v_mfma_f32_16x16x32_bf16 v[22:25], v[208:211], v[156:159], v[22:25]
	v_mfma_f32_16x16x32_bf16 v[18:21], v[212:215], v[156:159], v[18:21]
	v_mfma_f32_16x16x32_bf16 v[14:17], v[188:191], v[160:163], v[14:17]
	v_mfma_f32_16x16x32_bf16 v[10:13], v[192:195], v[160:163], v[10:13]
	v_mfma_f32_16x16x32_bf16 v[6:9], v[208:211], v[160:163], v[6:9]
	v_mfma_f32_16x16x32_bf16 v[2:5], v[212:215], v[160:163], v[2:5]
	v_mfma_f32_16x16x32_bf16 v[66:69], v[188:191], v[164:167], v[66:69]
	v_mfma_f32_16x16x32_bf16 v[70:73], v[192:195], v[164:167], v[70:73]
	v_mfma_f32_16x16x32_bf16 v[74:77], v[208:211], v[164:167], v[74:77]
	v_mfma_f32_16x16x32_bf16 v[78:81], v[212:215], v[164:167], v[78:81]
	v_mfma_f32_16x16x32_bf16 v[82:85], v[188:191], v[168:171], v[82:85]
	v_mfma_f32_16x16x32_bf16 v[86:89], v[192:195], v[168:171], v[86:89]
	v_mfma_f32_16x16x32_bf16 v[90:93], v[208:211], v[168:171], v[90:93]
	v_mfma_f32_16x16x32_bf16 v[94:97], v[212:215], v[168:171], v[94:97]
	v_mfma_f32_16x16x32_bf16 v[98:101], v[188:191], v[174:177], v[98:101]
	v_mfma_f32_16x16x32_bf16 v[102:105], v[192:195], v[174:177], v[102:105]
	v_mfma_f32_16x16x32_bf16 v[106:109], v[208:211], v[174:177], v[106:109]
	v_mfma_f32_16x16x32_bf16 v[110:113], v[212:215], v[174:177], v[110:113]
	v_mfma_f32_16x16x32_bf16 v[114:117], v[188:191], v[182:185], v[114:117]
	v_mfma_f32_16x16x32_bf16 v[118:121], v[192:195], v[182:185], v[118:121]
	v_mfma_f32_16x16x32_bf16 v[122:125], v[208:211], v[182:185], v[122:125]
	v_mfma_f32_16x16x32_bf16 v[126:129], v[212:215], v[182:185], v[126:129]
	s_setprio 0
	s_add_i32 s37, s37, -1
	s_cmp_lg_u32 s37, 0
	s_cbranch_scc1 .Lr2o_k
	s_waitcnt vmcnt(0)
	s_barrier
	s_add_i32 m0, s36, 0xc000
	s_nop 0
	global_load_lds_dwordx4 v136, s[34:35]
	s_add_i32 m0, s36, 0xd000
	s_nop 0
	global_load_lds_dwordx4 v137, s[34:35]
	s_add_i32 m0, s36, 0xe000
	s_nop 0
	global_load_lds_dwordx4 v138, s[34:35]
	s_add_i32 m0, s36, 0xf000
	s_nop 0
	global_load_lds_dwordx4 v139, s[34:35]
	s_add_u32 s34, s34, 0x80
	s_addc_u32 s35, s35, 0
	ds_read_b128 v[148:151], v140 offset:0
	ds_read_b128 v[152:155], v140 offset:2048
	ds_read_b128 v[156:159], v140 offset:4096
	ds_read_b128 v[160:163], v140 offset:6144
	ds_read_b128 v[164:167], v140 offset:16384
	ds_read_b128 v[168:171], v140 offset:18432
	ds_read_b128 v[174:177], v140 offset:20480
	ds_read_b128 v[182:185], v140 offset:22528
	ds_read_b128 v[188:191], v142 offset:32768
	ds_read_b128 v[192:195], v142 offset:34816
	ds_read_b128 v[208:211], v142 offset:36864
	ds_read_b128 v[212:215], v142 offset:38912
	s_waitcnt lgkmcnt(0)
	s_setprio 3
	v_mfma_f32_16x16x32_bf16 v[62:65], v[188:191], v[148:151], v[62:65]
	v_mfma_f32_16x16x32_bf16 v[58:61], v[192:195], v[148:151], v[58:61]
	v_mfma_f32_16x16x32_bf16 v[54:57], v[208:211], v[148:151], v[54:57]
	v_mfma_f32_16x16x32_bf16 v[50:53], v[212:215], v[148:151], v[50:53]
	v_mfma_f32_16x16x32_bf16 v[46:49], v[188:191], v[152:155], v[46:49]
	v_mfma_f32_16x16x32_bf16 v[42:45], v[192:195], v[152:155], v[42:45]
	v_mfma_f32_16x16x32_bf16 v[38:41], v[208:211], v[152:155], v[38:41]
	v_mfma_f32_16x16x32_bf16 v[34:37], v[212:215], v[152:155], v[34:37]
	v_mfma_f32_16x16x32_bf16 v[30:33], v[188:191], v[156:159], v[30:33]
	v_mfma_f32_16x16x32_bf16 v[26:29], v[192:195], v[156:159], v[26:29]
	v_mfma_f32_16x16x32_bf16 v[22:25], v[208:211], v[156:159], v[22:25]
	v_mfma_f32_16x16x32_bf16 v[18:21], v[212:215], v[156:159], v[18:21]
	v_mfma_f32_16x16x32_bf16 v[14:17], v[188:191], v[160:163], v[14:17]
	v_mfma_f32_16x16x32_bf16 v[10:13], v[192:195], v[160:163], v[10:13]
	v_mfma_f32_16x16x32_bf16 v[6:9], v[208:211], v[160:163], v[6:9]
	v_mfma_f32_16x16x32_bf16 v[2:5], v[212:215], v[160:163], v[2:5]
	v_mfma_f32_16x16x32_bf16 v[66:69], v[188:191], v[164:167], v[66:69]
	v_mfma_f32_16x16x32_bf16 v[70:73], v[192:195], v[164:167], v[70:73]
	v_mfma_f32_16x16x32_bf16 v[74:77], v[208:211], v[164:167], v[74:77]
	v_mfma_f32_16x16x32_bf16 v[78:81], v[212:215], v[164:167], v[78:81]
	v_mfma_f32_16x16x32_bf16 v[82:85], v[188:191], v[168:171], v[82:85]
	v_mfma_f32_16x16x32_bf16 v[86:89], v[192:195], v[168:171], v[86:89]
	v_mfma_f32_16x16x32_bf16 v[90:93], v[208:211], v[168:171], v[90:93]
	v_mfma_f32_16x16x32_bf16 v[94:97], v[212:215], v[168:171], v[94:97]
	v_mfma_f32_16x16x32_bf16 v[98:101], v[188:191], v[174:177], v[98:101]
	v_mfma_f32_16x16x32_bf16 v[102:105], v[192:195], v[174:177], v[102:105]
	v_mfma_f32_16x16x32_bf16 v[106:109], v[208:211], v[174:177], v[106:109]
	v_mfma_f32_16x16x32_bf16 v[110:113], v[212:215], v[174:177], v[110:113]
	v_mfma_f32_16x16x32_bf16 v[114:117], v[188:191], v[182:185], v[114:117]
	v_mfma_f32_16x16x32_bf16 v[118:121], v[192:195], v[182:185], v[118:121]
	v_mfma_f32_16x16x32_bf16 v[122:125], v[208:211], v[182:185], v[122:125]
	v_mfma_f32_16x16x32_bf16 v[126:129], v[212:215], v[182:185], v[126:129]
	s_setprio 0
	ds_read_b128 v[148:151], v141 offset:0
	ds_read_b128 v[152:155], v141 offset:2048
	ds_read_b128 v[156:159], v141 offset:4096
	ds_read_b128 v[160:163], v141 offset:6144
	ds_read_b128 v[164:167], v141 offset:16384
	ds_read_b128 v[168:171], v141 offset:18432
	ds_read_b128 v[174:177], v141 offset:20480
	ds_read_b128 v[182:185], v141 offset:22528
	ds_read_b128 v[188:191], v143 offset:32768
	ds_read_b128 v[192:195], v143 offset:34816
	ds_read_b128 v[208:211], v143 offset:36864
	ds_read_b128 v[212:215], v143 offset:38912
	s_waitcnt lgkmcnt(0)
	s_barrier
	s_add_i32 m0, s36, 0x0
	s_nop 0
	global_load_lds_dwordx4 v136, s[30:31]
	s_add_i32 m0, s36, 0x1000
	s_nop 0
	global_load_lds_dwordx4 v137, s[30:31]
	s_add_i32 m0, s36, 0x2000
	s_nop 0
	global_load_lds_dwordx4 v138, s[30:31]
	s_add_i32 m0, s36, 0x3000
	s_nop 0
	global_load_lds_dwordx4 v139, s[30:31]
	s_add_i32 m0, s36, 0x4000
	s_nop 0
	global_load_lds_dwordx4 v136, s[44:45]
	s_add_i32 m0, s36, 0x5000
	s_nop 0
	global_load_lds_dwordx4 v137, s[44:45]
	s_add_i32 m0, s36, 0x6000
	s_nop 0
	global_load_lds_dwordx4 v138, s[44:45]
	s_add_i32 m0, s36, 0x7000
	s_nop 0
	global_load_lds_dwordx4 v139, s[44:45]
	s_add_u32 s30, s30, 0x80
	s_addc_u32 s31, s31, 0
	s_add_u32 s44, s44, 0x80
	s_addc_u32 s45, s45, 0
	s_setprio 3
	v_mfma_f32_16x16x32_bf16 v[62:65], v[188:191], v[148:151], v[62:65]
	v_mfma_f32_16x16x32_bf16 v[58:61], v[192:195], v[148:151], v[58:61]
	v_mfma_f32_16x16x32_bf16 v[54:57], v[208:211], v[148:151], v[54:57]
	v_mfma_f32_16x16x32_bf16 v[50:53], v[212:215], v[148:151], v[50:53]
	v_mfma_f32_16x16x32_bf16 v[46:49], v[188:191], v[152:155], v[46:49]
	v_mfma_f32_16x16x32_bf16 v[42:45], v[192:195], v[152:155], v[42:45]
	v_mfma_f32_16x16x32_bf16 v[38:41], v[208:211], v[152:155], v[38:41]
	v_mfma_f32_16x16x32_bf16 v[34:37], v[212:215], v[152:155], v[34:37]
	v_mfma_f32_16x16x32_bf16 v[30:33], v[188:191], v[156:159], v[30:33]
	v_mfma_f32_16x16x32_bf16 v[26:29], v[192:195], v[156:159], v[26:29]
	v_mfma_f32_16x16x32_bf16 v[22:25], v[208:211], v[156:159], v[22:25]
	v_mfma_f32_16x16x32_bf16 v[18:21], v[212:215], v[156:159], v[18:21]
	v_mfma_f32_16x16x32_bf16 v[14:17], v[188:191], v[160:163], v[14:17]
	v_mfma_f32_16x16x32_bf16 v[10:13], v[192:195], v[160:163], v[10:13]
	v_mfma_f32_16x16x32_bf16 v[6:9], v[208:211], v[160:163], v[6:9]
	v_mfma_f32_16x16x32_bf16 v[2:5], v[212:215], v[160:163], v[2:5]
	v_mfma_f32_16x16x32_bf16 v[66:69], v[188:191], v[164:167], v[66:69]
	v_mfma_f32_16x16x32_bf16 v[70:73], v[192:195], v[164:167], v[70:73]
	v_mfma_f32_16x16x32_bf16 v[74:77], v[208:211], v[164:167], v[74:77]
	v_mfma_f32_16x16x32_bf16 v[78:81], v[212:215], v[164:167], v[78:81]
	v_mfma_f32_16x16x32_bf16 v[82:85], v[188:191], v[168:171], v[82:85]
	v_mfma_f32_16x16x32_bf16 v[86:89], v[192:195], v[168:171], v[86:89]
	v_mfma_f32_16x16x32_bf16 v[90:93], v[208:211], v[168:171], v[90:93]
	v_mfma_f32_16x16x32_bf16 v[94:97], v[212:215], v[168:171], v[94:97]
	v_mfma_f32_16x16x32_bf16 v[98:101], v[188:191], v[174:177], v[98:101]
	v_mfma_f32_16x16x32_bf16 v[102:105], v[192:195], v[174:177], v[102:105]
	v_mfma_f32_16x16x32_bf16 v[106:109], v[208:211], v[174:177], v[106:109]
	v_mfma_f32_16x16x32_bf16 v[110:113], v[212:215], v[174:177], v[110:113]
	v_mfma_f32_16x16x32_bf16 v[114:117], v[188:191], v[182:185], v[114:117]
	v_mfma_f32_16x16x32_bf16 v[118:121], v[192:195], v[182:185], v[118:121]
	v_mfma_f32_16x16x32_bf16 v[122:125], v[208:211], v[182:185], v[122:125]
	v_mfma_f32_16x16x32_bf16 v[126:129], v[212:215], v[182:185], v[126:129]
	s_setprio 0
	s_waitcnt vmcnt(0)
	s_barrier
	ds_read_b128 v[148:151], v140 offset:0
	ds_read_b128 v[152:155], v140 offset:2048
	ds_read_b128 v[156:159], v140 offset:4096
	ds_read_b128 v[160:163], v140 offset:6144
	ds_read_b128 v[164:167], v140 offset:16384
	ds_read_b128 v[168:171], v140 offset:18432
	ds_read_b128 v[174:177], v140 offset:20480
	ds_read_b128 v[182:185], v140 offset:22528
	ds_read_b128 v[188:191], v142 offset:49152
	ds_read_b128 v[192:195], v142 offset:51200
	ds_read_b128 v[208:211], v142 offset:53248
	ds_read_b128 v[212:215], v142 offset:55296
	s_waitcnt lgkmcnt(0)
	s_setprio 3
	v_mfma_f32_16x16x32_bf16 v[62:65], v[188:191], v[148:151], v[62:65]
	v_mfma_f32_16x16x32_bf16 v[58:61], v[192:195], v[148:151], v[58:61]
	v_mfma_f32_16x16x32_bf16 v[54:57], v[208:211], v[148:151], v[54:57]
	v_mfma_f32_16x16x32_bf16 v[50:53], v[212:215], v[148:151], v[50:53]
	v_mfma_f32_16x16x32_bf16 v[46:49], v[188:191], v[152:155], v[46:49]
	v_mfma_f32_16x16x32_bf16 v[42:45], v[192:195], v[152:155], v[42:45]
	v_mfma_f32_16x16x32_bf16 v[38:41], v[208:211], v[152:155], v[38:41]
	v_mfma_f32_16x16x32_bf16 v[34:37], v[212:215], v[152:155], v[34:37]
	v_mfma_f32_16x16x32_bf16 v[30:33], v[188:191], v[156:159], v[30:33]
	v_mfma_f32_16x16x32_bf16 v[26:29], v[192:195], v[156:159], v[26:29]
	v_mfma_f32_16x16x32_bf16 v[22:25], v[208:211], v[156:159], v[22:25]
	v_mfma_f32_16x16x32_bf16 v[18:21], v[212:215], v[156:159], v[18:21]
	v_mfma_f32_16x16x32_bf16 v[14:17], v[188:191], v[160:163], v[14:17]
	v_mfma_f32_16x16x32_bf16 v[10:13], v[192:195], v[160:163], v[10:13]
	v_mfma_f32_16x16x32_bf16 v[6:9], v[208:211], v[160:163], v[6:9]
	v_mfma_f32_16x16x32_bf16 v[2:5], v[212:215], v[160:163], v[2:5]
	v_mfma_f32_16x16x32_bf16 v[66:69], v[188:191], v[164:167], v[66:69]
	v_mfma_f32_16x16x32_bf16 v[70:73], v[192:195], v[164:167], v[70:73]
	v_mfma_f32_16x16x32_bf16 v[74:77], v[208:211], v[164:167], v[74:77]
	v_mfma_f32_16x16x32_bf16 v[78:81], v[212:215], v[164:167], v[78:81]
	v_mfma_f32_16x16x32_bf16 v[82:85], v[188:191], v[168:171], v[82:85]
	v_mfma_f32_16x16x32_bf16 v[86:89], v[192:195], v[168:171], v[86:89]
	v_mfma_f32_16x16x32_bf16 v[90:93], v[208:211], v[168:171], v[90:93]
	v_mfma_f32_16x16x32_bf16 v[94:97], v[212:215], v[168:171], v[94:97]
	v_mfma_f32_16x16x32_bf16 v[98:101], v[188:191], v[174:177], v[98:101]
	v_mfma_f32_16x16x32_bf16 v[102:105], v[192:195], v[174:177], v[102:105]
	v_mfma_f32_16x16x32_bf16 v[106:109], v[208:211], v[174:177], v[106:109]
	v_mfma_f32_16x16x32_bf16 v[110:113], v[212:215], v[174:177], v[110:113]
	v_mfma_f32_16x16x32_bf16 v[114:117], v[188:191], v[182:185], v[114:117]
	v_mfma_f32_16x16x32_bf16 v[118:121], v[192:195], v[182:185], v[118:121]
	v_mfma_f32_16x16x32_bf16 v[122:125], v[208:211], v[182:185], v[122:125]
	v_mfma_f32_16x16x32_bf16 v[126:129], v[212:215], v[182:185], v[126:129]
	s_setprio 0
	ds_read_b128 v[148:151], v141 offset:0
	ds_read_b128 v[152:155], v141 offset:2048
	ds_read_b128 v[156:159], v141 offset:4096
	ds_read_b128 v[160:163], v141 offset:6144
	ds_read_b128 v[164:167], v141 offset:16384
	ds_read_b128 v[168:171], v141 offset:18432
	ds_read_b128 v[174:177], v141 offset:20480
	ds_read_b128 v[182:185], v141 offset:22528
	ds_read_b128 v[188:191], v143 offset:49152
	ds_read_b128 v[192:195], v143 offset:51200
	ds_read_b128 v[208:211], v143 offset:53248
	ds_read_b128 v[212:215], v143 offset:55296
	s_waitcnt lgkmcnt(0)
	s_setprio 3
	v_mfma_f32_16x16x32_bf16 v[62:65], v[188:191], v[148:151], v[62:65]
	v_mfma_f32_16x16x32_bf16 v[58:61], v[192:195], v[148:151], v[58:61]
	v_mfma_f32_16x16x32_bf16 v[54:57], v[208:211], v[148:151], v[54:57]
	v_mfma_f32_16x16x32_bf16 v[50:53], v[212:215], v[148:151], v[50:53]
	v_mfma_f32_16x16x32_bf16 v[46:49], v[188:191], v[152:155], v[46:49]
	v_mfma_f32_16x16x32_bf16 v[42:45], v[192:195], v[152:155], v[42:45]
	v_mfma_f32_16x16x32_bf16 v[38:41], v[208:211], v[152:155], v[38:41]
	v_mfma_f32_16x16x32_bf16 v[34:37], v[212:215], v[152:155], v[34:37]
	v_mfma_f32_16x16x32_bf16 v[30:33], v[188:191], v[156:159], v[30:33]
	v_mfma_f32_16x16x32_bf16 v[26:29], v[192:195], v[156:159], v[26:29]
	v_mfma_f32_16x16x32_bf16 v[22:25], v[208:211], v[156:159], v[22:25]
	v_mfma_f32_16x16x32_bf16 v[18:21], v[212:215], v[156:159], v[18:21]
	v_mfma_f32_16x16x32_bf16 v[14:17], v[188:191], v[160:163], v[14:17]
	v_mfma_f32_16x16x32_bf16 v[10:13], v[192:195], v[160:163], v[10:13]
	v_mfma_f32_16x16x32_bf16 v[6:9], v[208:211], v[160:163], v[6:9]
	v_mfma_f32_16x16x32_bf16 v[2:5], v[212:215], v[160:163], v[2:5]
	v_mfma_f32_16x16x32_bf16 v[66:69], v[188:191], v[164:167], v[66:69]
	v_mfma_f32_16x16x32_bf16 v[70:73], v[192:195], v[164:167], v[70:73]
	v_mfma_f32_16x16x32_bf16 v[74:77], v[208:211], v[164:167], v[74:77]
	v_mfma_f32_16x16x32_bf16 v[78:81], v[212:215], v[164:167], v[78:81]
	v_mfma_f32_16x16x32_bf16 v[82:85], v[188:191], v[168:171], v[82:85]
	v_mfma_f32_16x16x32_bf16 v[86:89], v[192:195], v[168:171], v[86:89]
	v_mfma_f32_16x16x32_bf16 v[90:93], v[208:211], v[168:171], v[90:93]
	v_mfma_f32_16x16x32_bf16 v[94:97], v[212:215], v[168:171], v[94:97]
	v_mfma_f32_16x16x32_bf16 v[98:101], v[188:191], v[174:177], v[98:101]
	v_mfma_f32_16x16x32_bf16 v[102:105], v[192:195], v[174:177], v[102:105]
	v_mfma_f32_16x16x32_bf16 v[106:109], v[208:211], v[174:177], v[106:109]
	v_mfma_f32_16x16x32_bf16 v[110:113], v[212:215], v[174:177], v[110:113]
	v_mfma_f32_16x16x32_bf16 v[114:117], v[188:191], v[182:185], v[114:117]
	v_mfma_f32_16x16x32_bf16 v[118:121], v[192:195], v[182:185], v[118:121]
	v_mfma_f32_16x16x32_bf16 v[122:125], v[208:211], v[182:185], v[122:125]
	v_mfma_f32_16x16x32_bf16 v[126:129], v[212:215], v[182:185], v[126:129]
	s_setprio 0
	v_lshrrev_b32_e32 v144, 7, v196
	v_and_b32_e32 v145, 15, v196
	v_lshl_or_b32 v144, v144, 6, v145
	v_lshlrev_b32_e32 v144, 12, v144
	v_bfe_u32 v145, v196, 6, 1
	v_bfe_u32 v146, v196, 4, 2
	v_lshlrev_b32_e32 v145, 8, v145
	v_lshl_or_b32 v145, v146, 4, v145
	v_add_u32_e32 v136, v144, v145
	v_add_u32_e32 v137, 0x10000, v136
	v_add_u32_e32 v138, 0x20000, v136
	v_add_u32_e32 v139, 0x30000, v136
	s_nop 7
	s_nop 7
	s_nop 7
	global_load_dwordx4 v[148:151], v136, s[40:41] offset:0
	global_load_dwordx4 v[152:155], v136, s[40:41] offset:64
	global_load_dwordx4 v[156:159], v136, s[40:41] offset:128
	global_load_dwordx4 v[160:163], v136, s[40:41] offset:192
	global_load_dwordx4 v[164:167], v137, s[40:41] offset:0
	global_load_dwordx4 v[168:171], v137, s[40:41] offset:64
	global_load_dwordx4 v[174:177], v137, s[40:41] offset:128
	global_load_dwordx4 v[182:185], v137, s[40:41] offset:192
	global_load_dwordx4 v[188:191], v138, s[40:41] offset:0
	global_load_dwordx4 v[192:195], v138, s[40:41] offset:64
	global_load_dwordx4 v[208:211], v138, s[40:41] offset:128
	global_load_dwordx4 v[212:215], v138, s[40:41] offset:192
	global_load_dwordx4 v[216:219], v139, s[40:41] offset:0
	global_load_dwordx4 v[220:223], v139, s[40:41] offset:64
	global_load_dwordx4 v[242:245], v139, s[40:41] offset:128
	global_load_dwordx4 v[144:147], v139, s[40:41] offset:192
	s_waitcnt vmcnt(0)
	v_pk_add_f32 v[62:63], v[62:63], v[148:149]
	v_pk_add_f32 v[64:65], v[64:65], v[150:151]
	v_pk_add_f32 v[58:59], v[58:59], v[152:153]
	v_pk_add_f32 v[60:61], v[60:61], v[154:155]
	v_pk_add_f32 v[54:55], v[54:55], v[156:157]
	v_pk_add_f32 v[56:57], v[56:57], v[158:159]
	v_pk_add_f32 v[50:51], v[50:51], v[160:161]
	v_pk_add_f32 v[52:53], v[52:53], v[162:163]
	v_pk_add_f32 v[46:47], v[46:47], v[164:165]
	v_pk_add_f32 v[48:49], v[48:49], v[166:167]
	v_pk_add_f32 v[42:43], v[42:43], v[168:169]
	v_pk_add_f32 v[44:45], v[44:45], v[170:171]
	v_pk_add_f32 v[38:39], v[38:39], v[174:175]
	v_pk_add_f32 v[40:41], v[40:41], v[176:177]
	v_pk_add_f32 v[34:35], v[34:35], v[182:183]
	v_pk_add_f32 v[36:37], v[36:37], v[184:185]
	v_pk_add_f32 v[30:31], v[30:31], v[188:189]
	v_pk_add_f32 v[32:33], v[32:33], v[190:191]
	v_pk_add_f32 v[26:27], v[26:27], v[192:193]
	v_pk_add_f32 v[28:29], v[28:29], v[194:195]
	v_pk_add_f32 v[22:23], v[22:23], v[208:209]
	v_pk_add_f32 v[24:25], v[24:25], v[210:211]
	v_pk_add_f32 v[18:19], v[18:19], v[212:213]
	v_pk_add_f32 v[20:21], v[20:21], v[214:215]
	v_pk_add_f32 v[14:15], v[14:15], v[216:217]
	v_pk_add_f32 v[16:17], v[16:17], v[218:219]
	v_pk_add_f32 v[10:11], v[10:11], v[220:221]
	v_pk_add_f32 v[12:13], v[12:13], v[222:223]
	v_pk_add_f32 v[6:7], v[6:7], v[242:243]
	v_pk_add_f32 v[8:9], v[8:9], v[244:245]
	v_pk_add_f32 v[2:3], v[2:3], v[144:145]
	v_pk_add_f32 v[4:5], v[4:5], v[146:147]
	global_load_dwordx4 v[148:151], v136, s[42:43] offset:0
	global_load_dwordx4 v[152:155], v136, s[42:43] offset:64
	global_load_dwordx4 v[156:159], v136, s[42:43] offset:128
	global_load_dwordx4 v[160:163], v136, s[42:43] offset:192
	global_load_dwordx4 v[164:167], v137, s[42:43] offset:0
	global_load_dwordx4 v[168:171], v137, s[42:43] offset:64
	global_load_dwordx4 v[174:177], v137, s[42:43] offset:128
	global_load_dwordx4 v[182:185], v137, s[42:43] offset:192
	global_load_dwordx4 v[188:191], v138, s[42:43] offset:0
	global_load_dwordx4 v[192:195], v138, s[42:43] offset:64
	global_load_dwordx4 v[208:211], v138, s[42:43] offset:128
	global_load_dwordx4 v[212:215], v138, s[42:43] offset:192
	global_load_dwordx4 v[216:219], v139, s[42:43] offset:0
	global_load_dwordx4 v[220:223], v139, s[42:43] offset:64
	global_load_dwordx4 v[242:245], v139, s[42:43] offset:128
	global_load_dwordx4 v[144:147], v139, s[42:43] offset:192
	global_store_dwordx4 v136, v[62:65], s[40:41] offset:0
	global_store_dwordx4 v136, v[58:61], s[40:41] offset:64
	global_store_dwordx4 v136, v[54:57], s[40:41] offset:128
	global_store_dwordx4 v136, v[50:53], s[40:41] offset:192
	global_store_dwordx4 v137, v[46:49], s[40:41] offset:0
	global_store_dwordx4 v137, v[42:45], s[40:41] offset:64
	global_store_dwordx4 v137, v[38:41], s[40:41] offset:128
	global_store_dwordx4 v137, v[34:37], s[40:41] offset:192
	global_store_dwordx4 v138, v[30:33], s[40:41] offset:0
	global_store_dwordx4 v138, v[26:29], s[40:41] offset:64
	global_store_dwordx4 v138, v[22:25], s[40:41] offset:128
	global_store_dwordx4 v138, v[18:21], s[40:41] offset:192
	global_store_dwordx4 v139, v[14:17], s[40:41] offset:0
	global_store_dwordx4 v139, v[10:13], s[40:41] offset:64
	global_store_dwordx4 v139, v[6:9], s[40:41] offset:128
	global_store_dwordx4 v139, v[2:5], s[40:41] offset:192
	s_waitcnt vmcnt(0)
	v_pk_add_f32 v[66:67], v[66:67], v[148:149]
	v_pk_add_f32 v[68:69], v[68:69], v[150:151]
	v_pk_add_f32 v[70:71], v[70:71], v[152:153]
	v_pk_add_f32 v[72:73], v[72:73], v[154:155]
	v_pk_add_f32 v[74:75], v[74:75], v[156:157]
	v_pk_add_f32 v[76:77], v[76:77], v[158:159]
	v_pk_add_f32 v[78:79], v[78:79], v[160:161]
	v_pk_add_f32 v[80:81], v[80:81], v[162:163]
	v_pk_add_f32 v[82:83], v[82:83], v[164:165]
	v_pk_add_f32 v[84:85], v[84:85], v[166:167]
	v_pk_add_f32 v[86:87], v[86:87], v[168:169]
	v_pk_add_f32 v[88:89], v[88:89], v[170:171]
	v_pk_add_f32 v[90:91], v[90:91], v[174:175]
	v_pk_add_f32 v[92:93], v[92:93], v[176:177]
	v_pk_add_f32 v[94:95], v[94:95], v[182:183]
	v_pk_add_f32 v[96:97], v[96:97], v[184:185]
	v_pk_add_f32 v[98:99], v[98:99], v[188:189]
	v_pk_add_f32 v[100:101], v[100:101], v[190:191]
	v_pk_add_f32 v[102:103], v[102:103], v[192:193]
	v_pk_add_f32 v[104:105], v[104:105], v[194:195]
	v_pk_add_f32 v[106:107], v[106:107], v[208:209]
	v_pk_add_f32 v[108:109], v[108:109], v[210:211]
	v_pk_add_f32 v[110:111], v[110:111], v[212:213]
	v_pk_add_f32 v[112:113], v[112:113], v[214:215]
	v_pk_add_f32 v[114:115], v[114:115], v[216:217]
	v_pk_add_f32 v[116:117], v[116:117], v[218:219]
	v_pk_add_f32 v[118:119], v[118:119], v[220:221]
	v_pk_add_f32 v[120:121], v[120:121], v[222:223]
	v_pk_add_f32 v[122:123], v[122:123], v[242:243]
	v_pk_add_f32 v[124:125], v[124:125], v[244:245]
	v_pk_add_f32 v[126:127], v[126:127], v[144:145]
	v_pk_add_f32 v[128:129], v[128:129], v[146:147]
	global_store_dwordx4 v136, v[66:69], s[42:43] offset:0
	global_store_dwordx4 v136, v[70:73], s[42:43] offset:64
	global_store_dwordx4 v136, v[74:77], s[42:43] offset:128
	global_store_dwordx4 v136, v[78:81], s[42:43] offset:192
	global_store_dwordx4 v137, v[82:85], s[42:43] offset:0
	global_store_dwordx4 v137, v[86:89], s[42:43] offset:64
	global_store_dwordx4 v137, v[90:93], s[42:43] offset:128
	global_store_dwordx4 v137, v[94:97], s[42:43] offset:192
	global_store_dwordx4 v138, v[98:101], s[42:43] offset:0
	global_store_dwordx4 v138, v[102:105], s[42:43] offset:64
	global_store_dwordx4 v138, v[106:109], s[42:43] offset:128
	global_store_dwordx4 v138, v[110:113], s[42:43] offset:192
	global_store_dwordx4 v139, v[114:117], s[42:43] offset:0
	global_store_dwordx4 v139, v[118:121], s[42:43] offset:64
	global_store_dwordx4 v139, v[122:125], s[42:43] offset:128
	global_store_dwordx4 v139, v[126:129], s[42:43] offset:192
	s_branch .LBB0_2421
